# adds batched residual-GEMM epilogues (W_o, FFN2): per column quarter all resid/LN loads issued together, counted waits, same packed arithmetic
# speedup vs baseline: 1.0280x; 1.0003x over previous
.Lk3_mid_128:
	s_setprio 1
	s_add_u32 s98, s42, s27
	s_addc_u32 s99, s43, 0
	s_add_u32 s98, s98, 0x80
	s_addc_u32 s99, s99, 0
	ds_read_b128 v[132:135], v127 offset:16384
	ds_read_b128 v[152:155], v127 offset:18432
	ds_read_b128 v[160:163], v127 offset:20480
	ds_read_b128 v[164:167], v127 offset:22528
	ds_read_b128 v[140:143], v129
	ds_read_b128 v[144:147], v129 offset:2048
	ds_read_b128 v[148:151], v129 offset:4096
	ds_read_b128 v[156:159], v129 offset:6144
	s_add_u32 m0, s100, 0x8000
	s_waitcnt lgkmcnt(3)
	v_mfma_f32_16x16x32_bf16 v[34:37], v[132:135], v[140:143], v[34:37]
	global_load_lds_dwordx4 v194, s[98:99]
	v_mfma_f32_16x16x32_bf16 v[94:97], v[152:155], v[140:143], v[94:97]
	ds_read_b128 v[198:201], v128
	s_add_u32 m0, s100, 0xc000
	v_mfma_f32_16x16x32_bf16 v[38:41], v[160:163], v[140:143], v[38:41]
	global_load_lds_dwordx4 v195, s[98:99]
	v_mfma_f32_16x16x32_bf16 v[90:93], v[164:167], v[140:143], v[90:93]
	ds_read_b128 v[140:143], v128 offset:2048
	s_add_u32 m0, s100, 0x9000
	s_waitcnt lgkmcnt(4)
	v_mfma_f32_16x16x32_bf16 v[42:45], v[132:135], v[144:147], v[42:45]
	global_load_lds_dwordx4 v196, s[98:99]
	v_mfma_f32_16x16x32_bf16 v[86:89], v[152:155], v[144:147], v[86:89]
	ds_read_b128 v[210:213], v128 offset:4096
	s_add_u32 m0, s100, 0xd000
	v_mfma_f32_16x16x32_bf16 v[46:49], v[160:163], v[144:147], v[46:49]
	global_load_lds_dwordx4 v197, s[98:99]
	v_mfma_f32_16x16x32_bf16 v[82:85], v[164:167], v[144:147], v[82:85]
	ds_read_b128 v[144:147], v128 offset:6144
	s_add_u32 m0, s100, 0xa000
	s_waitcnt lgkmcnt(5)
	v_mfma_f32_16x16x32_bf16 v[50:53], v[132:135], v[148:151], v[50:53]
	global_load_lds_dwordx4 v202, s[98:99]
	v_mfma_f32_16x16x32_bf16 v[78:81], v[152:155], v[148:151], v[78:81]
	ds_read_b128 v[222:225], v130 offset:16384
	s_add_u32 m0, s100, 0xe000
	v_mfma_f32_16x16x32_bf16 v[54:57], v[160:163], v[148:151], v[54:57]
	global_load_lds_dwordx4 v203, s[98:99]
	v_mfma_f32_16x16x32_bf16 v[70:73], v[164:167], v[148:151], v[70:73]
	ds_read_b128 v[148:151], v130 offset:18432
	s_add_u32 m0, s100, 0xb000
	s_waitcnt lgkmcnt(6)
	v_mfma_f32_16x16x32_bf16 v[58:61], v[132:135], v[156:159], v[58:61]
	global_load_lds_dwordx4 v204, s[98:99]
	v_mfma_f32_16x16x32_bf16 v[66:69], v[152:155], v[156:159], v[66:69]
	ds_read_b128 v[152:155], v130 offset:20480
	s_add_u32 m0, s100, 0xf000
	v_mfma_f32_16x16x32_bf16 v[62:65], v[160:163], v[156:159], v[62:65]
	global_load_lds_dwordx4 v205, s[98:99]
	v_mfma_f32_16x16x32_bf16 v[74:77], v[164:167], v[156:159], v[74:77]
	ds_read_b128 v[156:159], v130 offset:22528
	s_waitcnt lgkmcnt(3)
	v_mfma_f32_16x16x32_bf16 v[34:37], v[222:225], v[198:201], v[34:37]
	s_waitcnt lgkmcnt(2)
	v_mfma_f32_16x16x32_bf16 v[94:97], v[148:151], v[198:201], v[94:97]
	s_waitcnt lgkmcnt(1)
	v_mfma_f32_16x16x32_bf16 v[38:41], v[152:155], v[198:201], v[38:41]
	s_waitcnt lgkmcnt(0)
	v_mfma_f32_16x16x32_bf16 v[90:93], v[156:159], v[198:201], v[90:93]
	v_mfma_f32_16x16x32_bf16 v[42:45], v[222:225], v[140:143], v[42:45]
	v_mfma_f32_16x16x32_bf16 v[86:89], v[148:151], v[140:143], v[86:89]
	v_mfma_f32_16x16x32_bf16 v[46:49], v[152:155], v[140:143], v[46:49]
	v_mfma_f32_16x16x32_bf16 v[82:85], v[156:159], v[140:143], v[82:85]
	v_mfma_f32_16x16x32_bf16 v[50:53], v[222:225], v[210:213], v[50:53]
	v_mfma_f32_16x16x32_bf16 v[78:81], v[148:151], v[210:213], v[78:81]
	v_mfma_f32_16x16x32_bf16 v[54:57], v[152:155], v[210:213], v[54:57]
	v_mfma_f32_16x16x32_bf16 v[70:73], v[156:159], v[210:213], v[70:73]
	v_mfma_f32_16x16x32_bf16 v[58:61], v[222:225], v[144:147], v[58:61]
	v_mfma_f32_16x16x32_bf16 v[66:69], v[148:151], v[144:147], v[66:69]
	v_mfma_f32_16x16x32_bf16 v[62:65], v[152:155], v[144:147], v[62:65]
	v_mfma_f32_16x16x32_bf16 v[74:77], v[156:159], v[144:147], v[74:77]
	s_waitcnt vmcnt(0)
	s_setprio 0
	s_waitcnt lgkmcnt(0)
	s_barrier
	s_setprio 1
	s_add_u32 s98, s98, 0x80
	s_addc_u32 s99, s99, 0
	ds_read_b128 v[26:29], v127 offset:49152
	ds_read_b128 v[30:33], v127 offset:51200
	ds_read_b128 v[148:151], v127 offset:53248
	ds_read_b128 v[152:155], v127 offset:55296
	ds_read_b128 v[10:13], v129 offset:32768
	ds_read_b128 v[18:21], v129 offset:34816
	ds_read_b128 v[140:143], v129 offset:36864
	ds_read_b128 v[144:147], v129 offset:38912
	s_add_u32 m0, s100, 0x0
	s_waitcnt lgkmcnt(3)
	v_mfma_f32_16x16x32_bf16 v[34:37], v[26:29], v[10:13], v[34:37]
	global_load_lds_dwordx4 v194, s[98:99]
	v_mfma_f32_16x16x32_bf16 v[94:97], v[30:33], v[10:13], v[94:97]
	ds_read_b128 v[156:159], v128 offset:32768
	s_add_u32 m0, s100, 0x4000
	v_mfma_f32_16x16x32_bf16 v[38:41], v[148:151], v[10:13], v[38:41]
	global_load_lds_dwordx4 v195, s[98:99]
	v_mfma_f32_16x16x32_bf16 v[90:93], v[152:155], v[10:13], v[90:93]
	ds_read_b128 v[164:167], v128 offset:34816
	s_add_u32 m0, s100, 0x1000
	s_waitcnt lgkmcnt(4)
	v_mfma_f32_16x16x32_bf16 v[42:45], v[26:29], v[18:21], v[42:45]
	global_load_lds_dwordx4 v196, s[98:99]
	v_mfma_f32_16x16x32_bf16 v[86:89], v[30:33], v[18:21], v[86:89]
	ds_read_b128 v[198:201], v128 offset:36864
	s_add_u32 m0, s100, 0x5000
	v_mfma_f32_16x16x32_bf16 v[46:49], v[148:151], v[18:21], v[46:49]
	global_load_lds_dwordx4 v197, s[98:99]
	v_mfma_f32_16x16x32_bf16 v[82:85], v[152:155], v[18:21], v[82:85]
	ds_read_b128 v[210:213], v128 offset:38912
	s_add_u32 m0, s100, 0x2000
	s_waitcnt lgkmcnt(5)
	v_mfma_f32_16x16x32_bf16 v[50:53], v[26:29], v[140:143], v[50:53]
	global_load_lds_dwordx4 v202, s[98:99]
	v_mfma_f32_16x16x32_bf16 v[78:81], v[30:33], v[140:143], v[78:81]
	ds_read_b128 v[222:225], v130 offset:49152
	s_add_u32 m0, s100, 0x6000
	v_mfma_f32_16x16x32_bf16 v[54:57], v[148:151], v[140:143], v[54:57]
	global_load_lds_dwordx4 v203, s[98:99]
	v_mfma_f32_16x16x32_bf16 v[70:73], v[152:155], v[140:143], v[70:73]
	ds_read_b128 v[140:143], v130 offset:51200
	s_add_u32 m0, s100, 0x3000
	s_waitcnt lgkmcnt(6)
	v_mfma_f32_16x16x32_bf16 v[58:61], v[26:29], v[144:147], v[58:61]
	global_load_lds_dwordx4 v204, s[98:99]
	v_mfma_f32_16x16x32_bf16 v[66:69], v[30:33], v[144:147], v[66:69]
	ds_read_b128 v[230:233], v130 offset:53248
	s_add_u32 m0, s100, 0x7000
	v_mfma_f32_16x16x32_bf16 v[62:65], v[148:151], v[144:147], v[62:65]
	global_load_lds_dwordx4 v205, s[98:99]
	v_mfma_f32_16x16x32_bf16 v[74:77], v[152:155], v[144:147], v[74:77]
	ds_read_b128 v[144:147], v130 offset:55296
	s_waitcnt lgkmcnt(3)
	v_mfma_f32_16x16x32_bf16 v[34:37], v[222:225], v[156:159], v[34:37]
	s_waitcnt lgkmcnt(2)
	v_mfma_f32_16x16x32_bf16 v[94:97], v[140:143], v[156:159], v[94:97]
	s_waitcnt lgkmcnt(1)
	v_mfma_f32_16x16x32_bf16 v[38:41], v[230:233], v[156:159], v[38:41]
	s_waitcnt lgkmcnt(0)
	v_mfma_f32_16x16x32_bf16 v[90:93], v[144:147], v[156:159], v[90:93]
	v_mfma_f32_16x16x32_bf16 v[42:45], v[222:225], v[164:167], v[42:45]
	v_mfma_f32_16x16x32_bf16 v[86:89], v[140:143], v[164:167], v[86:89]
	v_mfma_f32_16x16x32_bf16 v[46:49], v[230:233], v[164:167], v[46:49]
	v_mfma_f32_16x16x32_bf16 v[82:85], v[144:147], v[164:167], v[82:85]
	v_mfma_f32_16x16x32_bf16 v[50:53], v[222:225], v[198:201], v[50:53]
	v_mfma_f32_16x16x32_bf16 v[78:81], v[140:143], v[198:201], v[78:81]
	v_mfma_f32_16x16x32_bf16 v[54:57], v[230:233], v[198:201], v[54:57]
	v_mfma_f32_16x16x32_bf16 v[70:73], v[144:147], v[198:201], v[70:73]
	v_mfma_f32_16x16x32_bf16 v[58:61], v[222:225], v[210:213], v[58:61]
	v_mfma_f32_16x16x32_bf16 v[66:69], v[140:143], v[210:213], v[66:69]
	v_mfma_f32_16x16x32_bf16 v[62:65], v[230:233], v[210:213], v[62:65]
	v_mfma_f32_16x16x32_bf16 v[74:77], v[144:147], v[210:213], v[74:77]
	s_waitcnt vmcnt(0)
	s_setprio 0
	s_add_i32 s8, s8, 2
	s_add_u32 s42, s42, 0x100
	s_addc_u32 s43, s43, 0
	s_cmp_lt_u32 s8, 38
	s_waitcnt lgkmcnt(0)
	s_barrier
	s_cbranch_scc1 .Lk3_mid_128
	s_setprio 1
	s_add_u32 s98, s42, s27
	s_addc_u32 s99, s43, 0
	s_add_u32 s98, s98, 0x80
	s_addc_u32 s99, s99, 0
	ds_read_b128 v[132:135], v127 offset:16384
	ds_read_b128 v[152:155], v127 offset:18432
	ds_read_b128 v[160:163], v127 offset:20480
	ds_read_b128 v[164:167], v127 offset:22528
	ds_read_b128 v[140:143], v129
	ds_read_b128 v[144:147], v129 offset:2048
	ds_read_b128 v[148:151], v129 offset:4096
	ds_read_b128 v[156:159], v129 offset:6144
	s_add_u32 m0, s100, 0x8000
	s_waitcnt lgkmcnt(3)
	v_mfma_f32_16x16x32_bf16 v[34:37], v[132:135], v[140:143], v[34:37]
	global_load_lds_dwordx4 v194, s[98:99]
	v_mfma_f32_16x16x32_bf16 v[94:97], v[152:155], v[140:143], v[94:97]
	ds_read_b128 v[198:201], v128
	s_add_u32 m0, s100, 0xc000
	v_mfma_f32_16x16x32_bf16 v[38:41], v[160:163], v[140:143], v[38:41]
	global_load_lds_dwordx4 v195, s[98:99]
	v_mfma_f32_16x16x32_bf16 v[90:93], v[164:167], v[140:143], v[90:93]
	ds_read_b128 v[140:143], v128 offset:2048
	s_add_u32 m0, s100, 0x9000
	s_waitcnt lgkmcnt(4)
	v_mfma_f32_16x16x32_bf16 v[42:45], v[132:135], v[144:147], v[42:45]
	global_load_lds_dwordx4 v196, s[98:99]
	v_mfma_f32_16x16x32_bf16 v[86:89], v[152:155], v[144:147], v[86:89]
	ds_read_b128 v[210:213], v128 offset:4096
	s_add_u32 m0, s100, 0xd000
	v_mfma_f32_16x16x32_bf16 v[46:49], v[160:163], v[144:147], v[46:49]
	global_load_lds_dwordx4 v197, s[98:99]
	v_mfma_f32_16x16x32_bf16 v[82:85], v[164:167], v[144:147], v[82:85]
	ds_read_b128 v[144:147], v128 offset:6144
	s_add_u32 m0, s100, 0xa000
	s_waitcnt lgkmcnt(5)
	v_mfma_f32_16x16x32_bf16 v[50:53], v[132:135], v[148:151], v[50:53]
	global_load_lds_dwordx4 v202, s[98:99]
	v_mfma_f32_16x16x32_bf16 v[78:81], v[152:155], v[148:151], v[78:81]
	ds_read_b128 v[222:225], v130 offset:16384
	s_add_u32 m0, s100, 0xe000
	v_mfma_f32_16x16x32_bf16 v[54:57], v[160:163], v[148:151], v[54:57]
	global_load_lds_dwordx4 v203, s[98:99]
	v_mfma_f32_16x16x32_bf16 v[70:73], v[164:167], v[148:151], v[70:73]
	ds_read_b128 v[148:151], v130 offset:18432
	s_add_u32 m0, s100, 0xb000
	s_waitcnt lgkmcnt(6)
	v_mfma_f32_16x16x32_bf16 v[58:61], v[132:135], v[156:159], v[58:61]
	global_load_lds_dwordx4 v204, s[98:99]
	v_mfma_f32_16x16x32_bf16 v[66:69], v[152:155], v[156:159], v[66:69]
	ds_read_b128 v[152:155], v130 offset:20480
	s_add_u32 m0, s100, 0xf000
	v_mfma_f32_16x16x32_bf16 v[62:65], v[160:163], v[156:159], v[62:65]
	global_load_lds_dwordx4 v205, s[98:99]
	v_mfma_f32_16x16x32_bf16 v[74:77], v[164:167], v[156:159], v[74:77]
	ds_read_b128 v[156:159], v130 offset:22528
	s_waitcnt lgkmcnt(3)
	v_mfma_f32_16x16x32_bf16 v[34:37], v[222:225], v[198:201], v[34:37]
	s_waitcnt lgkmcnt(2)
	v_mfma_f32_16x16x32_bf16 v[94:97], v[148:151], v[198:201], v[94:97]
	s_waitcnt lgkmcnt(1)
	v_mfma_f32_16x16x32_bf16 v[38:41], v[152:155], v[198:201], v[38:41]
	s_waitcnt lgkmcnt(0)
	v_mfma_f32_16x16x32_bf16 v[90:93], v[156:159], v[198:201], v[90:93]
	v_mfma_f32_16x16x32_bf16 v[42:45], v[222:225], v[140:143], v[42:45]
	v_mfma_f32_16x16x32_bf16 v[86:89], v[148:151], v[140:143], v[86:89]
	v_mfma_f32_16x16x32_bf16 v[46:49], v[152:155], v[140:143], v[46:49]
	v_mfma_f32_16x16x32_bf16 v[82:85], v[156:159], v[140:143], v[82:85]
	v_mfma_f32_16x16x32_bf16 v[50:53], v[222:225], v[210:213], v[50:53]
	v_mfma_f32_16x16x32_bf16 v[78:81], v[148:151], v[210:213], v[78:81]
	v_mfma_f32_16x16x32_bf16 v[54:57], v[152:155], v[210:213], v[54:57]
	v_mfma_f32_16x16x32_bf16 v[70:73], v[156:159], v[210:213], v[70:73]
	v_mfma_f32_16x16x32_bf16 v[58:61], v[222:225], v[144:147], v[58:61]
	v_mfma_f32_16x16x32_bf16 v[66:69], v[148:151], v[144:147], v[66:69]
	v_mfma_f32_16x16x32_bf16 v[62:65], v[152:155], v[144:147], v[62:65]
	v_mfma_f32_16x16x32_bf16 v[74:77], v[156:159], v[144:147], v[74:77]
	s_waitcnt vmcnt(0)
	s_setprio 0
	s_waitcnt lgkmcnt(0)
	s_barrier
	s_setprio 1
	s_add_u32 s98, s98, 0x80
	s_addc_u32 s99, s99, 0
	ds_read_b128 v[26:29], v127 offset:49152
	ds_read_b128 v[30:33], v127 offset:51200
	ds_read_b128 v[148:151], v127 offset:53248
	ds_read_b128 v[152:155], v127 offset:55296
	ds_read_b128 v[10:13], v129 offset:32768
	ds_read_b128 v[18:21], v129 offset:34816
	ds_read_b128 v[140:143], v129 offset:36864
	ds_read_b128 v[144:147], v129 offset:38912
	s_add_u32 m0, s100, 0x0
	s_waitcnt lgkmcnt(3)
	v_mfma_f32_16x16x32_bf16 v[34:37], v[26:29], v[10:13], v[34:37]
	global_load_lds_dwordx4 v194, s[98:99]
	v_mfma_f32_16x16x32_bf16 v[94:97], v[30:33], v[10:13], v[94:97]
	ds_read_b128 v[156:159], v128 offset:32768
	s_add_u32 m0, s100, 0x4000
	v_mfma_f32_16x16x32_bf16 v[38:41], v[148:151], v[10:13], v[38:41]
	global_load_lds_dwordx4 v195, s[98:99]
	v_mfma_f32_16x16x32_bf16 v[90:93], v[152:155], v[10:13], v[90:93]
	ds_read_b128 v[164:167], v128 offset:34816
	s_add_u32 m0, s100, 0x1000
	s_waitcnt lgkmcnt(4)
	v_mfma_f32_16x16x32_bf16 v[42:45], v[26:29], v[18:21], v[42:45]
	global_load_lds_dwordx4 v196, s[98:99]
	v_mfma_f32_16x16x32_bf16 v[86:89], v[30:33], v[18:21], v[86:89]
	ds_read_b128 v[198:201], v128 offset:36864
	s_add_u32 m0, s100, 0x5000
	v_mfma_f32_16x16x32_bf16 v[46:49], v[148:151], v[18:21], v[46:49]
	global_load_lds_dwordx4 v197, s[98:99]
	v_mfma_f32_16x16x32_bf16 v[82:85], v[152:155], v[18:21], v[82:85]
	ds_read_b128 v[210:213], v128 offset:38912
	s_add_u32 m0, s100, 0x2000
	s_waitcnt lgkmcnt(5)
	v_mfma_f32_16x16x32_bf16 v[50:53], v[26:29], v[140:143], v[50:53]
	global_load_lds_dwordx4 v202, s[98:99]
	v_mfma_f32_16x16x32_bf16 v[78:81], v[30:33], v[140:143], v[78:81]
	ds_read_b128 v[222:225], v130 offset:49152
	s_add_u32 m0, s100, 0x6000
	v_mfma_f32_16x16x32_bf16 v[54:57], v[148:151], v[140:143], v[54:57]
	global_load_lds_dwordx4 v203, s[98:99]
	v_mfma_f32_16x16x32_bf16 v[70:73], v[152:155], v[140:143], v[70:73]
	ds_read_b128 v[140:143], v130 offset:51200
	s_add_u32 m0, s100, 0x3000
	s_waitcnt lgkmcnt(6)
	v_mfma_f32_16x16x32_bf16 v[58:61], v[26:29], v[144:147], v[58:61]
	global_load_lds_dwordx4 v204, s[98:99]
	v_mfma_f32_16x16x32_bf16 v[66:69], v[30:33], v[144:147], v[66:69]
	ds_read_b128 v[230:233], v130 offset:53248
	s_add_u32 m0, s100, 0x7000
	v_mfma_f32_16x16x32_bf16 v[62:65], v[148:151], v[144:147], v[62:65]
	global_load_lds_dwordx4 v205, s[98:99]
	v_mfma_f32_16x16x32_bf16 v[74:77], v[152:155], v[144:147], v[74:77]
	ds_read_b128 v[144:147], v130 offset:55296
	s_waitcnt lgkmcnt(3)
	v_mfma_f32_16x16x32_bf16 v[34:37], v[222:225], v[156:159], v[34:37]
	global_load_dwordx4 v[2:5], v206, s[98:99] offset:128
	s_waitcnt lgkmcnt(2)
	v_mfma_f32_16x16x32_bf16 v[94:97], v[140:143], v[156:159], v[94:97]
	s_waitcnt lgkmcnt(1)
	v_mfma_f32_16x16x32_bf16 v[38:41], v[230:233], v[156:159], v[38:41]
	global_load_dwordx4 v[6:9], v207, s[98:99] offset:128
	s_waitcnt lgkmcnt(0)
	v_mfma_f32_16x16x32_bf16 v[90:93], v[144:147], v[156:159], v[90:93]
	v_mfma_f32_16x16x32_bf16 v[42:45], v[222:225], v[164:167], v[42:45]
	global_load_dwordx4 v[10:13], v208, s[98:99] offset:128
	v_mfma_f32_16x16x32_bf16 v[86:89], v[140:143], v[164:167], v[86:89]
	v_mfma_f32_16x16x32_bf16 v[46:49], v[230:233], v[164:167], v[46:49]
	global_load_dwordx4 v[14:17], v209, s[98:99] offset:128
	v_mfma_f32_16x16x32_bf16 v[82:85], v[144:147], v[164:167], v[82:85]
	v_mfma_f32_16x16x32_bf16 v[50:53], v[222:225], v[198:201], v[50:53]
	global_load_dwordx4 v[18:21], v214, s[98:99] offset:128
	v_mfma_f32_16x16x32_bf16 v[78:81], v[140:143], v[198:201], v[78:81]
	v_mfma_f32_16x16x32_bf16 v[54:57], v[230:233], v[198:201], v[54:57]
	global_load_dwordx4 v[22:25], v215, s[98:99] offset:128
	v_mfma_f32_16x16x32_bf16 v[70:73], v[144:147], v[198:201], v[70:73]
	v_mfma_f32_16x16x32_bf16 v[58:61], v[222:225], v[210:213], v[58:61]
	global_load_dwordx4 v[26:29], v216, s[98:99] offset:128
	v_mfma_f32_16x16x32_bf16 v[66:69], v[140:143], v[210:213], v[66:69]
	v_mfma_f32_16x16x32_bf16 v[62:65], v[230:233], v[210:213], v[62:65]
	global_load_dwordx4 v[30:33], v217, s[98:99] offset:128
	v_mfma_f32_16x16x32_bf16 v[74:77], v[144:147], v[210:213], v[74:77]
	s_waitcnt vmcnt(8)
	s_setprio 0
	s_add_i32 s8, s8, 2
	s_add_u32 s42, s42, 0x100
	s_addc_u32 s43, s43, 0
	s_waitcnt lgkmcnt(0)
	s_barrier
	s_add_i32 s8, s11, s2
	s_cmpk_lt_u32 s8, 0x100
	s_cselect_b32 s10, s8, s11
	s_lshr_b32 s9, s10, 3
	s_and_b32 s9, s9, 0x1fffff8
	s_add_i32 s9, s9, s21
	s_and_b32 s11, s10, 7
	s_or_b32 s9, s9, s11
	v_mov_b32_e32 v0, v169
	s_lshl_b32 s9, s9, 7
	s_movk_i32 s11, 0xb00
	v_lshrrev_b32_e32 v98, 3, v0
	v_add_u32_e32 v98, s9, v98
	v_lshlrev_b32_e32 v0, 3, v0
	v_mul_lo_u32 v98, v98, s11
	s_lshl_b32 s10, s10, 4
	v_and_or_b32 v0, v0, 56, v98
	v_mov_b32_e32 v98, v169
	s_and_b32 s10, s10, 0x380
	s_cmpk_gt_u32 s8, 0xff
	v_lshrrev_b32_e32 v99, 3, v98
	v_add_u32_e32 v99, s10, v99
	v_lshlrev_b32_e32 v98, 3, v98
	v_mul_lo_u32 v99, v99, s11
	v_and_or_b32 v164, v98, 56, v99
	v_add_u32_e32 v114, 0x16000, v0
	v_add_u32_e32 v124, 0x2c000, v0
	v_add_u32_e32 v136, 0x42000, v0
	v_add_u32_e32 v174, 0x16000, v164
	v_add_u32_e32 v176, 0x2c000, v164
	v_add_u32_e32 v178, 0x42000, v164
	s_setprio 1
	ds_read_b128 v[98:101], v127 offset:16384
	ds_read_b128 v[110:113], v127 offset:18432
	ds_read_b128 v[144:147], v127 offset:20480
	ds_read_b128 v[148:151], v127 offset:22528
	ds_read_b128 v[102:105], v129
	ds_read_b128 v[106:109], v129 offset:2048
	ds_read_b128 v[132:135], v129 offset:4096
	ds_read_b128 v[140:143], v129 offset:6144
	v_readlane_b32 s14, v254, 33
	v_readlane_b32 s15, v254, 34
	v_mov_b32_e32 v165, v1
	v_mov_b32_e32 v115, v1
	v_mov_b32_e32 v175, v1
	v_mov_b32_e32 v125, v1
	v_mov_b32_e32 v177, v1
	v_mov_b32_e32 v137, v1
	v_mov_b32_e32 v179, v1
	v_lshl_add_u64 v[180:181], v[0:1], 1, s[14:15]
	v_lshl_add_u64 v[186:187], v[164:165], 1, s[38:39]
	v_lshl_add_u64 v[114:115], v[114:115], 1, s[14:15]
	v_lshl_add_u64 v[174:175], v[174:175], 1, s[38:39]
	v_lshl_add_u64 v[188:189], v[124:125], 1, s[14:15]
	v_lshl_add_u64 v[176:177], v[176:177], 1, s[38:39]
	v_lshl_add_u64 v[136:137], v[136:137], 1, s[14:15]
	v_lshl_add_u64 v[178:179], v[178:179], 1, s[38:39]
	s_waitcnt lgkmcnt(3)
	v_mfma_f32_16x16x32_bf16 v[152:155], v[98:101], v[102:105], v[34:37]
	s_nop 2
	global_load_dwordx4 v[34:37], v[180:181], off
	v_mfma_f32_16x16x32_bf16 v[94:97], v[110:113], v[102:105], v[94:97]
	ds_read_b128 v[156:159], v128
	v_mfma_f32_16x16x32_bf16 v[160:163], v[144:147], v[102:105], v[38:41]
	s_nop 2
	global_load_dwordx4 v[38:41], v[186:187], off
	v_mfma_f32_16x16x32_bf16 v[90:93], v[148:151], v[102:105], v[90:93]
	ds_read_b128 v[102:105], v128 offset:2048
	s_waitcnt lgkmcnt(4)
	v_mfma_f32_16x16x32_bf16 v[164:167], v[98:101], v[106:109], v[42:45]
	s_nop 2
	global_load_dwordx4 v[42:45], v[114:115], off
	v_mfma_f32_16x16x32_bf16 v[86:89], v[110:113], v[106:109], v[86:89]
	ds_read_b128 v[194:197], v128 offset:4096
	v_mfma_f32_16x16x32_bf16 v[198:201], v[144:147], v[106:109], v[46:49]
	s_nop 2
	global_load_dwordx4 v[46:49], v[174:175], off
	v_mfma_f32_16x16x32_bf16 v[82:85], v[148:151], v[106:109], v[82:85]
	ds_read_b128 v[106:109], v128 offset:6144
	s_waitcnt lgkmcnt(5)
	v_mfma_f32_16x16x32_bf16 v[202:205], v[98:101], v[132:135], v[50:53]
	s_nop 2
	global_load_dwordx4 v[50:53], v[188:189], off
	v_mfma_f32_16x16x32_bf16 v[78:81], v[110:113], v[132:135], v[78:81]
	ds_read_b128 v[206:209], v130 offset:16384
	v_mfma_f32_16x16x32_bf16 v[210:213], v[144:147], v[132:135], v[54:57]
	s_nop 2
	global_load_dwordx4 v[54:57], v[176:177], off
	v_mfma_f32_16x16x32_bf16 v[70:73], v[148:151], v[132:135], v[70:73]
	ds_read_b128 v[132:135], v130 offset:18432
	s_waitcnt lgkmcnt(6)
	v_mfma_f32_16x16x32_bf16 v[98:101], v[98:101], v[140:143], v[58:61]
	s_nop 2
	global_load_dwordx4 v[58:61], v[136:137], off
	v_mfma_f32_16x16x32_bf16 v[66:69], v[110:113], v[140:143], v[66:69]
	ds_read_b128 v[110:113], v130 offset:20480
	v_mfma_f32_16x16x32_bf16 v[144:147], v[144:147], v[140:143], v[62:65]
	s_nop 2
	global_load_dwordx4 v[62:65], v[178:179], off
	v_mfma_f32_16x16x32_bf16 v[74:77], v[148:151], v[140:143], v[74:77]
	ds_read_b128 v[140:143], v130 offset:22528
	s_waitcnt lgkmcnt(3)
	v_mfma_f32_16x16x32_bf16 v[148:151], v[206:209], v[156:159], v[152:155]
	s_waitcnt vmcnt(15)
	ds_write_b128 v122, v[2:5] offset:32768
	s_waitcnt lgkmcnt(3)
	v_mfma_f32_16x16x32_bf16 v[94:97], v[132:135], v[156:159], v[94:97]
	s_waitcnt lgkmcnt(2)
	v_mfma_f32_16x16x32_bf16 v[152:155], v[110:113], v[156:159], v[160:163]
	s_waitcnt vmcnt(14)
	ds_write_b128 v121, v[6:9] offset:49152
	s_waitcnt lgkmcnt(2)
	v_mfma_f32_16x16x32_bf16 v[90:93], v[140:143], v[156:159], v[90:93]
	v_mfma_f32_16x16x32_bf16 v[156:159], v[206:209], v[102:105], v[164:167]
	s_waitcnt vmcnt(13)
	ds_write_b128 v122, v[10:13] offset:36864
	v_mfma_f32_16x16x32_bf16 v[86:89], v[132:135], v[102:105], v[86:89]
	v_mfma_f32_16x16x32_bf16 v[160:163], v[110:113], v[102:105], v[198:201]
	s_waitcnt vmcnt(12)
	ds_write_b128 v121, v[14:17] offset:53248
	v_mfma_f32_16x16x32_bf16 v[82:85], v[140:143], v[102:105], v[82:85]
	v_mfma_f32_16x16x32_bf16 v[102:105], v[206:209], v[194:197], v[202:205]
	s_waitcnt vmcnt(11)
	ds_write_b128 v122, v[18:21] offset:40960
	v_mfma_f32_16x16x32_bf16 v[78:81], v[132:135], v[194:197], v[78:81]
	v_mfma_f32_16x16x32_bf16 v[164:167], v[110:113], v[194:197], v[210:213]
	s_waitcnt vmcnt(10)
	ds_write_b128 v121, v[22:25] offset:57344
	v_mfma_f32_16x16x32_bf16 v[70:73], v[140:143], v[194:197], v[70:73]
	v_mfma_f32_16x16x32_bf16 v[98:101], v[206:209], v[106:109], v[98:101]
	s_waitcnt vmcnt(9)
	ds_write_b128 v122, v[26:29] offset:45056
	v_mfma_f32_16x16x32_bf16 v[66:69], v[132:135], v[106:109], v[66:69]
	v_mfma_f32_16x16x32_bf16 v[110:113], v[110:113], v[106:109], v[144:147]
	s_waitcnt vmcnt(8)
	ds_write_b128 v121, v[30:33] offset:61440
	v_mfma_f32_16x16x32_bf16 v[74:77], v[140:143], v[106:109], v[74:77]
	s_setprio 0
	s_waitcnt lgkmcnt(0)
	s_barrier
	s_setprio 1
	ds_read_b128 v[26:29], v127 offset:49152
	ds_read_b128 v[30:33], v127 offset:51200
	ds_read_b128 v[132:135], v127 offset:53248
	ds_read_b128 v[140:143], v127 offset:55296
	ds_read_b128 v[10:13], v129 offset:32768
	ds_read_b128 v[18:21], v129 offset:34816
	ds_read_b128 v[106:109], v129 offset:36864
	ds_read_b128 v[122:125], v129 offset:38912
	s_waitcnt lgkmcnt(3)
	v_mfma_f32_16x16x32_bf16 v[144:147], v[26:29], v[10:13], v[148:151]
	global_load_dwordx4 v[2:5], v[180:181], off offset:128
	v_mfma_f32_16x16x32_bf16 v[94:97], v[30:33], v[10:13], v[94:97]
	s_nop 0
	ds_read_b128 v[148:151], v128 offset:32768
	v_mfma_f32_16x16x32_bf16 v[152:155], v[132:135], v[10:13], v[152:155]
	global_load_dwordx4 v[6:9], v[186:187], off offset:128
	v_mfma_f32_16x16x32_bf16 v[90:93], v[140:143], v[10:13], v[90:93]
	ds_read_b128 v[194:197], v128 offset:34816
	s_waitcnt lgkmcnt(4)
	v_mfma_f32_16x16x32_bf16 v[156:159], v[26:29], v[18:21], v[156:159]
	global_load_dwordx4 v[10:13], v[114:115], off offset:128
	v_mfma_f32_16x16x32_bf16 v[86:89], v[30:33], v[18:21], v[86:89]
	ds_read_b128 v[198:201], v128 offset:36864
	v_mfma_f32_16x16x32_bf16 v[160:163], v[132:135], v[18:21], v[160:163]
	global_load_dwordx4 v[14:17], v[174:175], off offset:128
	v_mfma_f32_16x16x32_bf16 v[82:85], v[140:143], v[18:21], v[82:85]
	ds_read_b128 v[126:129], v128 offset:38912
	s_waitcnt lgkmcnt(5)
	v_mfma_f32_16x16x32_bf16 v[202:205], v[26:29], v[106:109], v[102:105]
	global_load_dwordx4 v[18:21], v[188:189], off offset:128
	v_mfma_f32_16x16x32_bf16 v[78:81], v[30:33], v[106:109], v[78:81]
	ds_read_b128 v[206:209], v130 offset:49152
	v_mfma_f32_16x16x32_bf16 v[164:167], v[132:135], v[106:109], v[164:167]
	global_load_dwordx4 v[22:25], v[176:177], off offset:128
	v_mfma_f32_16x16x32_bf16 v[70:73], v[140:143], v[106:109], v[70:73]
	ds_read_b128 v[210:213], v130 offset:51200
	s_waitcnt lgkmcnt(6)
	v_mfma_f32_16x16x32_bf16 v[214:217], v[26:29], v[122:125], v[98:101]
	global_load_dwordx4 v[26:29], v[136:137], off offset:128
	v_mfma_f32_16x16x32_bf16 v[66:69], v[30:33], v[122:125], v[66:69]
	ds_read_b128 v[218:221], v130 offset:53248
	v_mfma_f32_16x16x32_bf16 v[110:113], v[132:135], v[122:125], v[110:113]
	global_load_dwordx4 v[30:33], v[178:179], off offset:128
	v_mfma_f32_16x16x32_bf16 v[122:125], v[140:143], v[122:125], v[74:77]
	s_waitcnt lgkmcnt(2)
	v_mfma_f32_16x16x32_bf16 v[132:135], v[206:209], v[148:151], v[144:147]
	s_waitcnt lgkmcnt(0)
	v_mfma_f32_16x16x32_bf16 v[144:147], v[218:221], v[148:151], v[152:155]
	s_nop 2
	ds_read_b128 v[152:155], v130 offset:55296
	v_mfma_f32_16x16x32_bf16 v[140:143], v[210:213], v[148:151], v[94:97]
	s_waitcnt lgkmcnt(0)
	v_mfma_f32_16x16x32_bf16 v[148:151], v[152:155], v[148:151], v[90:93]
	v_mfma_f32_16x16x32_bf16 v[98:101], v[152:155], v[194:197], v[82:85]
	v_mfma_f32_16x16x32_bf16 v[90:93], v[210:213], v[198:201], v[78:81]
	v_mfma_f32_16x16x32_bf16 v[82:85], v[152:155], v[198:201], v[70:73]
	v_mfma_f32_16x16x32_bf16 v[78:81], v[206:209], v[126:129], v[214:217]
	v_mfma_f32_16x16x32_bf16 v[74:77], v[210:213], v[126:129], v[66:69]
	v_mfma_f32_16x16x32_bf16 v[66:69], v[218:221], v[126:129], v[110:113]
	v_mfma_f32_16x16x32_bf16 v[70:73], v[152:155], v[126:129], v[122:125]
	v_mfma_f32_16x16x32_bf16 v[156:159], v[206:209], v[194:197], v[156:159]
	v_mfma_f32_16x16x32_bf16 v[106:109], v[210:213], v[194:197], v[86:89]
	v_mfma_f32_16x16x32_bf16 v[102:105], v[218:221], v[194:197], v[160:163]
	v_mfma_f32_16x16x32_bf16 v[94:97], v[206:209], v[198:201], v[202:205]
	v_mfma_f32_16x16x32_bf16 v[86:89], v[218:221], v[198:201], v[164:167]
	s_setprio 0
	v_add_u32_e32 v110, s4, v116
	v_ashrrev_i32_e32 v111, 31, v110
	v_readlane_b32 s44, v253, 18
	v_lshlrev_b64 v[112:113], 12, v[110:111]
	v_or_b32_e32 v0, s5, v117
	v_readlane_b32 s58, v253, 32
	v_readlane_b32 s59, v253, 33
	v_lshlrev_b64 v[114:115], 2, v[0:1]
	v_lshl_add_u64 v[166:167], v[110:111], 3, s[0:1]
	v_lshl_add_u64 v[112:113], s[58:59], 0, v[112:113]
	v_lshl_add_u64 v[164:165], v[112:113], 0, v[114:115]
	s_barrier
	v_readlane_b32 s44, v253, 18
	v_readlane_b32 s45, v253, 19
	v_readlane_b32 s46, v253, 20
	v_readlane_b32 s47, v253, 21
	v_readlane_b32 s48, v253, 22
	v_readlane_b32 s49, v253, 23
	v_readlane_b32 s50, v253, 24
	v_readlane_b32 s51, v253, 25
	v_readlane_b32 s52, v253, 26
	v_readlane_b32 s53, v253, 27
	v_readlane_b32 s54, v253, 28
	v_readlane_b32 s55, v253, 29
	v_readlane_b32 s56, v253, 30
	v_readlane_b32 s57, v253, 31
	v_readlane_b32 s58, v253, 32
	v_readlane_b32 s59, v253, 33
	s_mov_b64 s[42:43], -1
	v_or_b32_e32 v0, s5, v117
	v_lshlrev_b32_e32 v0, 2, v0
	v_add_u32_e32 v110, s4, v116
	v_lshlrev_b32_e32 v160, 3, v110
	v_lshlrev_b32_e32 v110, 12, v110
	v_add_u32_e32 v110, v110, v0
	v_add_u32_e32 v111, s4, v118
	v_lshlrev_b32_e32 v222, 3, v111
	v_lshlrev_b32_e32 v111, 12, v111
	v_add_u32_e32 v111, v111, v0
	v_add_u32_e32 v112, s4, v119
	v_lshlrev_b32_e32 v226, 3, v112
	v_lshlrev_b32_e32 v112, 12, v112
	v_add_u32_e32 v112, v112, v0
	v_add_u32_e32 v113, s4, v120
	v_lshlrev_b32_e32 v230, 3, v113
	v_lshlrev_b32_e32 v113, 12, v113
	v_add_u32_e32 v113, v113, v0
	s_mov_b32 s14, 0x3fb504f3
	global_load_dwordx2 v[114:115], v160, s[0:1]
	global_load_dwordx2 v[122:123], v222, s[0:1]
	global_load_dwordx2 v[124:125], v226, s[0:1]
	global_load_dwordx2 v[126:127], v230, s[0:1]
	global_load_dwordx4 v[128:131], v0, s[34:35]
	global_load_dwordx4 v[152:155], v0, s[40:41]
	global_load_dwordx4 v[160:163], v110, s[58:59]
	global_load_dwordx4 v[222:225], v111, s[58:59]
	global_load_dwordx4 v[226:229], v112, s[58:59]
	global_load_dwordx4 v[230:233], v113, s[58:59]
	s_waitcnt vmcnt(3)
	v_pk_add_f32 v[160:161], v[160:161], v[114:115] op_sel_hi:[1,0] neg_lo:[0,1] neg_hi:[0,1]
	v_pk_add_f32 v[162:163], v[162:163], v[114:115] op_sel_hi:[1,0] neg_lo:[0,1] neg_hi:[0,1]
	v_pk_mul_f32 v[160:161], v[160:161], v[114:115] op_sel:[0,1]
	v_pk_mul_f32 v[162:163], v[162:163], v[114:115] op_sel:[0,1]
	v_pk_fma_f32 v[160:161], v[160:161], v[128:129], v[152:153]
	v_pk_fma_f32 v[162:163], v[162:163], v[130:131], v[154:155]
	v_pk_fma_f32 v[132:133], v[160:161], s[14:15], v[132:133] op_sel_hi:[1,0,1]
	v_pk_fma_f32 v[134:135], v[162:163], s[14:15], v[134:135] op_sel_hi:[1,0,1]
	global_store_dwordx4 v110, v[132:135], s[58:59]
	s_waitcnt vmcnt(3)
	v_pk_add_f32 v[222:223], v[222:223], v[122:123] op_sel_hi:[1,0] neg_lo:[0,1] neg_hi:[0,1]
	v_pk_add_f32 v[224:225], v[224:225], v[122:123] op_sel_hi:[1,0] neg_lo:[0,1] neg_hi:[0,1]
	v_pk_mul_f32 v[222:223], v[222:223], v[122:123] op_sel:[0,1]
	v_pk_mul_f32 v[224:225], v[224:225], v[122:123] op_sel:[0,1]
	v_pk_fma_f32 v[222:223], v[222:223], v[128:129], v[152:153]
	v_pk_fma_f32 v[224:225], v[224:225], v[130:131], v[154:155]
	v_pk_fma_f32 v[156:157], v[222:223], s[14:15], v[156:157] op_sel_hi:[1,0,1]
	v_pk_fma_f32 v[158:159], v[224:225], s[14:15], v[158:159] op_sel_hi:[1,0,1]
	global_store_dwordx4 v111, v[156:159], s[58:59]
	s_waitcnt vmcnt(3)
	v_pk_add_f32 v[226:227], v[226:227], v[124:125] op_sel_hi:[1,0] neg_lo:[0,1] neg_hi:[0,1]
	v_pk_add_f32 v[228:229], v[228:229], v[124:125] op_sel_hi:[1,0] neg_lo:[0,1] neg_hi:[0,1]
	v_pk_mul_f32 v[226:227], v[226:227], v[124:125] op_sel:[0,1]
	v_pk_mul_f32 v[228:229], v[228:229], v[124:125] op_sel:[0,1]
	v_pk_fma_f32 v[226:227], v[226:227], v[128:129], v[152:153]
	v_pk_fma_f32 v[228:229], v[228:229], v[130:131], v[154:155]
	v_pk_fma_f32 v[94:95], v[226:227], s[14:15], v[94:95] op_sel_hi:[1,0,1]
	v_pk_fma_f32 v[96:97], v[228:229], s[14:15], v[96:97] op_sel_hi:[1,0,1]
	global_store_dwordx4 v112, v[94:97], s[58:59]
	s_waitcnt vmcnt(3)
	v_pk_add_f32 v[230:231], v[230:231], v[126:127] op_sel_hi:[1,0] neg_lo:[0,1] neg_hi:[0,1]
	v_pk_add_f32 v[232:233], v[232:233], v[126:127] op_sel_hi:[1,0] neg_lo:[0,1] neg_hi:[0,1]
	v_pk_mul_f32 v[230:231], v[230:231], v[126:127] op_sel:[0,1]
	v_pk_mul_f32 v[232:233], v[232:233], v[126:127] op_sel:[0,1]
	v_pk_fma_f32 v[230:231], v[230:231], v[128:129], v[152:153]
	v_pk_fma_f32 v[232:233], v[232:233], v[130:131], v[154:155]
	v_pk_fma_f32 v[78:79], v[230:231], s[14:15], v[78:79] op_sel_hi:[1,0,1]
	v_pk_fma_f32 v[80:81], v[232:233], s[14:15], v[80:81] op_sel_hi:[1,0,1]
	global_store_dwordx4 v113, v[78:81], s[58:59]
	global_load_dwordx4 v[128:131], v0, s[34:35] offset:16
	global_load_dwordx4 v[152:155], v0, s[40:41] offset:16
	global_load_dwordx4 v[160:163], v110, s[58:59] offset:16
	global_load_dwordx4 v[222:225], v111, s[58:59] offset:16
	global_load_dwordx4 v[226:229], v112, s[58:59] offset:16
	global_load_dwordx4 v[230:233], v113, s[58:59] offset:16
	s_waitcnt vmcnt(3)
	v_pk_add_f32 v[160:161], v[160:161], v[114:115] op_sel_hi:[1,0] neg_lo:[0,1] neg_hi:[0,1]
	v_pk_add_f32 v[162:163], v[162:163], v[114:115] op_sel_hi:[1,0] neg_lo:[0,1] neg_hi:[0,1]
	v_pk_mul_f32 v[160:161], v[160:161], v[114:115] op_sel:[0,1]
	v_pk_mul_f32 v[162:163], v[162:163], v[114:115] op_sel:[0,1]
	v_pk_fma_f32 v[160:161], v[160:161], v[128:129], v[152:153]
	v_pk_fma_f32 v[162:163], v[162:163], v[130:131], v[154:155]
	v_pk_fma_f32 v[140:141], v[160:161], s[14:15], v[140:141] op_sel_hi:[1,0,1]
	v_pk_fma_f32 v[142:143], v[162:163], s[14:15], v[142:143] op_sel_hi:[1,0,1]
	global_store_dwordx4 v110, v[140:143], s[58:59] offset:16
	s_waitcnt vmcnt(3)
	v_pk_add_f32 v[222:223], v[222:223], v[122:123] op_sel_hi:[1,0] neg_lo:[0,1] neg_hi:[0,1]
	v_pk_add_f32 v[224:225], v[224:225], v[122:123] op_sel_hi:[1,0] neg_lo:[0,1] neg_hi:[0,1]
	v_pk_mul_f32 v[222:223], v[222:223], v[122:123] op_sel:[0,1]
	v_pk_mul_f32 v[224:225], v[224:225], v[122:123] op_sel:[0,1]
	v_pk_fma_f32 v[222:223], v[222:223], v[128:129], v[152:153]
	v_pk_fma_f32 v[224:225], v[224:225], v[130:131], v[154:155]
	v_pk_fma_f32 v[106:107], v[222:223], s[14:15], v[106:107] op_sel_hi:[1,0,1]
	v_pk_fma_f32 v[108:109], v[224:225], s[14:15], v[108:109] op_sel_hi:[1,0,1]
	global_store_dwordx4 v111, v[106:109], s[58:59] offset:16
	s_waitcnt vmcnt(3)
	v_pk_add_f32 v[226:227], v[226:227], v[124:125] op_sel_hi:[1,0] neg_lo:[0,1] neg_hi:[0,1]
	v_pk_add_f32 v[228:229], v[228:229], v[124:125] op_sel_hi:[1,0] neg_lo:[0,1] neg_hi:[0,1]
	v_pk_mul_f32 v[226:227], v[226:227], v[124:125] op_sel:[0,1]
	v_pk_mul_f32 v[228:229], v[228:229], v[124:125] op_sel:[0,1]
	v_pk_fma_f32 v[226:227], v[226:227], v[128:129], v[152:153]
	v_pk_fma_f32 v[228:229], v[228:229], v[130:131], v[154:155]
	v_pk_fma_f32 v[90:91], v[226:227], s[14:15], v[90:91] op_sel_hi:[1,0,1]
	v_pk_fma_f32 v[92:93], v[228:229], s[14:15], v[92:93] op_sel_hi:[1,0,1]
	global_store_dwordx4 v112, v[90:93], s[58:59] offset:16
	s_waitcnt vmcnt(3)
	v_pk_add_f32 v[230:231], v[230:231], v[126:127] op_sel_hi:[1,0] neg_lo:[0,1] neg_hi:[0,1]
	v_pk_add_f32 v[232:233], v[232:233], v[126:127] op_sel_hi:[1,0] neg_lo:[0,1] neg_hi:[0,1]
	v_pk_mul_f32 v[230:231], v[230:231], v[126:127] op_sel:[0,1]
	v_pk_mul_f32 v[232:233], v[232:233], v[126:127] op_sel:[0,1]
	v_pk_fma_f32 v[230:231], v[230:231], v[128:129], v[152:153]
	v_pk_fma_f32 v[232:233], v[232:233], v[130:131], v[154:155]
	v_pk_fma_f32 v[74:75], v[230:231], s[14:15], v[74:75] op_sel_hi:[1,0,1]
	v_pk_fma_f32 v[76:77], v[232:233], s[14:15], v[76:77] op_sel_hi:[1,0,1]
	global_store_dwordx4 v113, v[74:77], s[58:59] offset:16
	global_load_dwordx4 v[128:131], v0, s[34:35] offset:128
	global_load_dwordx4 v[152:155], v0, s[40:41] offset:128
	global_load_dwordx4 v[160:163], v110, s[58:59] offset:128
	global_load_dwordx4 v[222:225], v111, s[58:59] offset:128
	global_load_dwordx4 v[226:229], v112, s[58:59] offset:128
	global_load_dwordx4 v[230:233], v113, s[58:59] offset:128
	s_waitcnt vmcnt(3)
	v_pk_add_f32 v[160:161], v[160:161], v[114:115] op_sel_hi:[1,0] neg_lo:[0,1] neg_hi:[0,1]
	v_pk_add_f32 v[162:163], v[162:163], v[114:115] op_sel_hi:[1,0] neg_lo:[0,1] neg_hi:[0,1]
	v_pk_mul_f32 v[160:161], v[160:161], v[114:115] op_sel:[0,1]
	v_pk_mul_f32 v[162:163], v[162:163], v[114:115] op_sel:[0,1]
	v_pk_fma_f32 v[160:161], v[160:161], v[128:129], v[152:153]
	v_pk_fma_f32 v[162:163], v[162:163], v[130:131], v[154:155]
	v_pk_fma_f32 v[144:145], v[160:161], s[14:15], v[144:145] op_sel_hi:[1,0,1]
	v_pk_fma_f32 v[146:147], v[162:163], s[14:15], v[146:147] op_sel_hi:[1,0,1]
	global_store_dwordx4 v110, v[144:147], s[58:59] offset:128
	s_waitcnt vmcnt(3)
	v_pk_add_f32 v[222:223], v[222:223], v[122:123] op_sel_hi:[1,0] neg_lo:[0,1] neg_hi:[0,1]
	v_pk_add_f32 v[224:225], v[224:225], v[122:123] op_sel_hi:[1,0] neg_lo:[0,1] neg_hi:[0,1]
	v_pk_mul_f32 v[222:223], v[222:223], v[122:123] op_sel:[0,1]
	v_pk_mul_f32 v[224:225], v[224:225], v[122:123] op_sel:[0,1]
	v_pk_fma_f32 v[222:223], v[222:223], v[128:129], v[152:153]
	v_pk_fma_f32 v[224:225], v[224:225], v[130:131], v[154:155]
	v_pk_fma_f32 v[102:103], v[222:223], s[14:15], v[102:103] op_sel_hi:[1,0,1]
	v_pk_fma_f32 v[104:105], v[224:225], s[14:15], v[104:105] op_sel_hi:[1,0,1]
	global_store_dwordx4 v111, v[102:105], s[58:59] offset:128
	s_waitcnt vmcnt(3)
	v_pk_add_f32 v[226:227], v[226:227], v[124:125] op_sel_hi:[1,0] neg_lo:[0,1] neg_hi:[0,1]
	v_pk_add_f32 v[228:229], v[228:229], v[124:125] op_sel_hi:[1,0] neg_lo:[0,1] neg_hi:[0,1]
	v_pk_mul_f32 v[226:227], v[226:227], v[124:125] op_sel:[0,1]
	v_pk_mul_f32 v[228:229], v[228:229], v[124:125] op_sel:[0,1]
	v_pk_fma_f32 v[226:227], v[226:227], v[128:129], v[152:153]
	v_pk_fma_f32 v[228:229], v[228:229], v[130:131], v[154:155]
	v_pk_fma_f32 v[86:87], v[226:227], s[14:15], v[86:87] op_sel_hi:[1,0,1]
	v_pk_fma_f32 v[88:89], v[228:229], s[14:15], v[88:89] op_sel_hi:[1,0,1]
	global_store_dwordx4 v112, v[86:89], s[58:59] offset:128
	s_waitcnt vmcnt(3)
	v_pk_add_f32 v[230:231], v[230:231], v[126:127] op_sel_hi:[1,0] neg_lo:[0,1] neg_hi:[0,1]
	v_pk_add_f32 v[232:233], v[232:233], v[126:127] op_sel_hi:[1,0] neg_lo:[0,1] neg_hi:[0,1]
	v_pk_mul_f32 v[230:231], v[230:231], v[126:127] op_sel:[0,1]
	v_pk_mul_f32 v[232:233], v[232:233], v[126:127] op_sel:[0,1]
	v_pk_fma_f32 v[230:231], v[230:231], v[128:129], v[152:153]
	v_pk_fma_f32 v[232:233], v[232:233], v[130:131], v[154:155]
	v_pk_fma_f32 v[66:67], v[230:231], s[14:15], v[66:67] op_sel_hi:[1,0,1]
	v_pk_fma_f32 v[68:69], v[232:233], s[14:15], v[68:69] op_sel_hi:[1,0,1]
	global_store_dwordx4 v113, v[66:69], s[58:59] offset:128
	global_load_dwordx4 v[128:131], v0, s[34:35] offset:144
	global_load_dwordx4 v[152:155], v0, s[40:41] offset:144
	global_load_dwordx4 v[160:163], v110, s[58:59] offset:144
	global_load_dwordx4 v[222:225], v111, s[58:59] offset:144
	global_load_dwordx4 v[226:229], v112, s[58:59] offset:144
	global_load_dwordx4 v[230:233], v113, s[58:59] offset:144
	s_waitcnt vmcnt(3)
	v_pk_add_f32 v[160:161], v[160:161], v[114:115] op_sel_hi:[1,0] neg_lo:[0,1] neg_hi:[0,1]
	v_pk_add_f32 v[162:163], v[162:163], v[114:115] op_sel_hi:[1,0] neg_lo:[0,1] neg_hi:[0,1]
	v_pk_mul_f32 v[160:161], v[160:161], v[114:115] op_sel:[0,1]
	v_pk_mul_f32 v[162:163], v[162:163], v[114:115] op_sel:[0,1]
	v_pk_fma_f32 v[160:161], v[160:161], v[128:129], v[152:153]
	v_pk_fma_f32 v[162:163], v[162:163], v[130:131], v[154:155]
	v_pk_fma_f32 v[148:149], v[160:161], s[14:15], v[148:149] op_sel_hi:[1,0,1]
	v_pk_fma_f32 v[150:151], v[162:163], s[14:15], v[150:151] op_sel_hi:[1,0,1]
	global_store_dwordx4 v110, v[148:151], s[58:59] offset:144
	s_waitcnt vmcnt(3)
	v_pk_add_f32 v[222:223], v[222:223], v[122:123] op_sel_hi:[1,0] neg_lo:[0,1] neg_hi:[0,1]
	v_pk_add_f32 v[224:225], v[224:225], v[122:123] op_sel_hi:[1,0] neg_lo:[0,1] neg_hi:[0,1]
	v_pk_mul_f32 v[222:223], v[222:223], v[122:123] op_sel:[0,1]
	v_pk_mul_f32 v[224:225], v[224:225], v[122:123] op_sel:[0,1]
	v_pk_fma_f32 v[222:223], v[222:223], v[128:129], v[152:153]
	v_pk_fma_f32 v[224:225], v[224:225], v[130:131], v[154:155]
	v_pk_fma_f32 v[98:99], v[222:223], s[14:15], v[98:99] op_sel_hi:[1,0,1]
	v_pk_fma_f32 v[100:101], v[224:225], s[14:15], v[100:101] op_sel_hi:[1,0,1]
	global_store_dwordx4 v111, v[98:101], s[58:59] offset:144
	s_waitcnt vmcnt(3)
	v_pk_add_f32 v[226:227], v[226:227], v[124:125] op_sel_hi:[1,0] neg_lo:[0,1] neg_hi:[0,1]
	v_pk_add_f32 v[228:229], v[228:229], v[124:125] op_sel_hi:[1,0] neg_lo:[0,1] neg_hi:[0,1]
	v_pk_mul_f32 v[226:227], v[226:227], v[124:125] op_sel:[0,1]
	v_pk_mul_f32 v[228:229], v[228:229], v[124:125] op_sel:[0,1]
	v_pk_fma_f32 v[226:227], v[226:227], v[128:129], v[152:153]
	v_pk_fma_f32 v[228:229], v[228:229], v[130:131], v[154:155]
	v_pk_fma_f32 v[82:83], v[226:227], s[14:15], v[82:83] op_sel_hi:[1,0,1]
	v_pk_fma_f32 v[84:85], v[228:229], s[14:15], v[84:85] op_sel_hi:[1,0,1]
	global_store_dwordx4 v112, v[82:85], s[58:59] offset:144
	s_waitcnt vmcnt(3)
	v_pk_add_f32 v[230:231], v[230:231], v[126:127] op_sel_hi:[1,0] neg_lo:[0,1] neg_hi:[0,1]
	v_pk_add_f32 v[232:233], v[232:233], v[126:127] op_sel_hi:[1,0] neg_lo:[0,1] neg_hi:[0,1]
	v_pk_mul_f32 v[230:231], v[230:231], v[126:127] op_sel:[0,1]
	v_pk_mul_f32 v[232:233], v[232:233], v[126:127] op_sel:[0,1]
	v_pk_fma_f32 v[230:231], v[230:231], v[128:129], v[152:153]
	v_pk_fma_f32 v[232:233], v[232:233], v[130:131], v[154:155]
	v_pk_fma_f32 v[70:71], v[230:231], s[14:15], v[70:71] op_sel_hi:[1,0,1]
	v_pk_fma_f32 v[72:73], v[232:233], s[14:15], v[72:73] op_sel_hi:[1,0,1]
	global_store_dwordx4 v113, v[70:73], s[58:59] offset:144
	s_cbranch_scc1 .LBB0_126
	v_mov_b32_e32 v0, v169
	v_mov_b32_e32 v67, v169
	s_movk_i32 s4, 0xb00
	v_lshrrev_b32_e32 v66, 3, v0
	v_lshrrev_b32_e32 v69, 3, v67
	v_add_u32_e32 v66, s9, v66
	v_add_u32_e32 v69, s10, v69
	v_lshlrev_b32_e32 v0, 3, v0
	v_mul_lo_u32 v66, v66, s4
	v_lshlrev_b32_e32 v67, 3, v67
	v_mul_lo_u32 v69, v69, s4
	v_and_or_b32 v0, v0, 56, v66
	v_and_or_b32 v72, v67, 56, v69
	v_add_u32_e32 v66, 0x16000, v0
	v_add_u32_e32 v68, 0x2c000, v0
	v_add_u32_e32 v70, 0x42000, v0
	v_add_u32_e32 v74, 0x16000, v72
	v_add_u32_e32 v76, 0x2c000, v72
	v_add_u32_e32 v78, 0x42000, v72
	s_mov_b64 s[42:43], 0
	s_branch .LBB0_126

.Lk3_mid_157:
	s_setprio 1
	s_add_u32 s98, s38, s36
	s_addc_u32 s99, s39, 0
	s_add_u32 s98, s98, 0x80
	s_addc_u32 s99, s99, 0
	v_add_u32_e32 v122, v119, v118
	v_add_u32_e32 v124, v119, v120
	v_add_u32_e32 v123, v121, v120
	ds_read_b128 v[126:129], v122 offset:16384
	ds_read_b128 v[144:147], v122 offset:18432
	ds_read_b128 v[158:161], v122 offset:20480
	ds_read_b128 v[162:165], v122 offset:22528
	ds_read_b128 v[130:133], v124
	ds_read_b128 v[134:137], v124 offset:2048
	ds_read_b128 v[140:143], v124 offset:4096
	ds_read_b128 v[148:151], v124 offset:6144
	s_add_u32 m0, s100, 0x8000
	s_waitcnt lgkmcnt(3)
	v_mfma_f32_16x16x32_bf16 v[34:37], v[126:129], v[130:133], v[34:37]
	global_load_lds_dwordx4 v194, s[98:99]
	v_mfma_f32_16x16x32_bf16 v[94:97], v[144:147], v[130:133], v[94:97]
	ds_read_b128 v[198:201], v123
	s_add_u32 m0, s100, 0xc000
	v_mfma_f32_16x16x32_bf16 v[38:41], v[158:161], v[130:133], v[38:41]
	global_load_lds_dwordx4 v195, s[98:99]
	v_mfma_f32_16x16x32_bf16 v[90:93], v[162:165], v[130:133], v[90:93]
	ds_read_b128 v[206:209], v123 offset:2048
	s_add_u32 m0, s100, 0x9000
	s_waitcnt lgkmcnt(4)
	v_mfma_f32_16x16x32_bf16 v[42:45], v[126:129], v[134:137], v[42:45]
	global_load_lds_dwordx4 v196, s[98:99]
	v_mfma_f32_16x16x32_bf16 v[86:89], v[144:147], v[134:137], v[86:89]
	ds_read_b128 v[214:217], v123 offset:4096
	s_add_u32 m0, s100, 0xd000
	v_mfma_f32_16x16x32_bf16 v[46:49], v[158:161], v[134:137], v[46:49]
	global_load_lds_dwordx4 v197, s[98:99]
	v_mfma_f32_16x16x32_bf16 v[82:85], v[162:165], v[134:137], v[82:85]
	v_add_u32_e32 v130, v121, v118
	ds_read_b128 v[132:135], v123 offset:6144
	s_add_u32 m0, s100, 0xa000
	s_waitcnt lgkmcnt(5)
	v_mfma_f32_16x16x32_bf16 v[50:53], v[126:129], v[140:143], v[50:53]
	global_load_lds_dwordx4 v202, s[98:99]
	v_mfma_f32_16x16x32_bf16 v[78:81], v[144:147], v[140:143], v[78:81]
	ds_read_b128 v[226:229], v130 offset:16384
	s_add_u32 m0, s100, 0xe000
	v_mfma_f32_16x16x32_bf16 v[54:57], v[158:161], v[140:143], v[54:57]
	global_load_lds_dwordx4 v203, s[98:99]
	v_mfma_f32_16x16x32_bf16 v[70:73], v[162:165], v[140:143], v[70:73]
	ds_read_b128 v[140:143], v130 offset:18432
	s_add_u32 m0, s100, 0xb000
	s_waitcnt lgkmcnt(6)
	v_mfma_f32_16x16x32_bf16 v[58:61], v[126:129], v[148:151], v[58:61]
	global_load_lds_dwordx4 v204, s[98:99]
	v_mfma_f32_16x16x32_bf16 v[66:69], v[144:147], v[148:151], v[66:69]
	ds_read_b128 v[144:147], v130 offset:20480
	s_add_u32 m0, s100, 0xf000
	v_mfma_f32_16x16x32_bf16 v[62:65], v[158:161], v[148:151], v[62:65]
	global_load_lds_dwordx4 v205, s[98:99]
	v_mfma_f32_16x16x32_bf16 v[74:77], v[162:165], v[148:151], v[74:77]
	ds_read_b128 v[148:151], v130 offset:22528
	s_waitcnt lgkmcnt(3)
	v_mfma_f32_16x16x32_bf16 v[34:37], v[226:229], v[198:201], v[34:37]
	s_waitcnt lgkmcnt(2)
	v_mfma_f32_16x16x32_bf16 v[94:97], v[140:143], v[198:201], v[94:97]
	s_waitcnt lgkmcnt(1)
	v_mfma_f32_16x16x32_bf16 v[38:41], v[144:147], v[198:201], v[38:41]
	s_waitcnt lgkmcnt(0)
	v_mfma_f32_16x16x32_bf16 v[90:93], v[148:151], v[198:201], v[90:93]
	v_mfma_f32_16x16x32_bf16 v[42:45], v[226:229], v[206:209], v[42:45]
	v_mfma_f32_16x16x32_bf16 v[86:89], v[140:143], v[206:209], v[86:89]
	v_mfma_f32_16x16x32_bf16 v[46:49], v[144:147], v[206:209], v[46:49]
	v_mfma_f32_16x16x32_bf16 v[82:85], v[148:151], v[206:209], v[82:85]
	v_mfma_f32_16x16x32_bf16 v[50:53], v[226:229], v[214:217], v[50:53]
	v_mfma_f32_16x16x32_bf16 v[78:81], v[140:143], v[214:217], v[78:81]
	v_mfma_f32_16x16x32_bf16 v[54:57], v[144:147], v[214:217], v[54:57]
	v_mfma_f32_16x16x32_bf16 v[70:73], v[148:151], v[214:217], v[70:73]
	v_mfma_f32_16x16x32_bf16 v[58:61], v[226:229], v[132:135], v[58:61]
	v_mfma_f32_16x16x32_bf16 v[66:69], v[140:143], v[132:135], v[66:69]
	v_mfma_f32_16x16x32_bf16 v[62:65], v[144:147], v[132:135], v[62:65]
	v_mfma_f32_16x16x32_bf16 v[74:77], v[148:151], v[132:135], v[74:77]
	s_waitcnt vmcnt(0)
	s_setprio 0
	s_waitcnt lgkmcnt(0)
	s_barrier
	s_setprio 1
	s_add_u32 s98, s98, 0x80
	s_addc_u32 s99, s99, 0
	ds_read_b128 v[26:29], v122 offset:49152
	ds_read_b128 v[30:33], v122 offset:51200
	ds_read_b128 v[144:147], v122 offset:53248
	ds_read_b128 v[148:151], v122 offset:55296
	ds_read_b128 v[10:13], v124 offset:32768
	ds_read_b128 v[18:21], v124 offset:34816
	ds_read_b128 v[132:135], v124 offset:36864
	ds_read_b128 v[140:143], v124 offset:38912
	s_add_u32 m0, s100, 0x0
	s_waitcnt lgkmcnt(3)
	v_mfma_f32_16x16x32_bf16 v[34:37], v[26:29], v[10:13], v[34:37]
	global_load_lds_dwordx4 v194, s[98:99]
	v_mfma_f32_16x16x32_bf16 v[94:97], v[30:33], v[10:13], v[94:97]
	ds_read_b128 v[162:165], v123 offset:32768
	s_add_u32 m0, s100, 0x4000
	v_mfma_f32_16x16x32_bf16 v[38:41], v[144:147], v[10:13], v[38:41]
	global_load_lds_dwordx4 v195, s[98:99]
	v_mfma_f32_16x16x32_bf16 v[90:93], v[148:151], v[10:13], v[90:93]
	ds_read_b128 v[198:201], v123 offset:34816
	s_add_u32 m0, s100, 0x1000
	s_waitcnt lgkmcnt(4)
	v_mfma_f32_16x16x32_bf16 v[42:45], v[26:29], v[18:21], v[42:45]
	global_load_lds_dwordx4 v196, s[98:99]
	v_mfma_f32_16x16x32_bf16 v[86:89], v[30:33], v[18:21], v[86:89]
	ds_read_b128 v[206:209], v123 offset:36864
	s_add_u32 m0, s100, 0x5000
	v_mfma_f32_16x16x32_bf16 v[46:49], v[144:147], v[18:21], v[46:49]
	global_load_lds_dwordx4 v197, s[98:99]
	v_mfma_f32_16x16x32_bf16 v[82:85], v[148:151], v[18:21], v[82:85]
	ds_read_b128 v[214:217], v123 offset:38912
	s_add_u32 m0, s100, 0x2000
	s_waitcnt lgkmcnt(5)
	v_mfma_f32_16x16x32_bf16 v[50:53], v[26:29], v[132:135], v[50:53]
	global_load_lds_dwordx4 v202, s[98:99]
	v_mfma_f32_16x16x32_bf16 v[78:81], v[30:33], v[132:135], v[78:81]
	ds_read_b128 v[226:229], v130 offset:49152
	s_add_u32 m0, s100, 0x6000
	v_mfma_f32_16x16x32_bf16 v[54:57], v[144:147], v[132:135], v[54:57]
	global_load_lds_dwordx4 v203, s[98:99]
	v_mfma_f32_16x16x32_bf16 v[70:73], v[148:151], v[132:135], v[70:73]
	ds_read_b128 v[132:135], v130 offset:51200
	s_add_u32 m0, s100, 0x3000
	s_waitcnt lgkmcnt(6)
	v_mfma_f32_16x16x32_bf16 v[58:61], v[26:29], v[140:143], v[58:61]
	global_load_lds_dwordx4 v204, s[98:99]
	v_mfma_f32_16x16x32_bf16 v[66:69], v[30:33], v[140:143], v[66:69]
	ds_read_b128 v[234:237], v130 offset:53248
	s_add_u32 m0, s100, 0x7000
	v_mfma_f32_16x16x32_bf16 v[62:65], v[144:147], v[140:143], v[62:65]
	global_load_lds_dwordx4 v205, s[98:99]
	v_mfma_f32_16x16x32_bf16 v[74:77], v[148:151], v[140:143], v[74:77]
	ds_read_b128 v[140:143], v130 offset:55296
	s_waitcnt lgkmcnt(3)
	v_mfma_f32_16x16x32_bf16 v[34:37], v[226:229], v[162:165], v[34:37]
	s_waitcnt lgkmcnt(2)
	v_mfma_f32_16x16x32_bf16 v[94:97], v[132:135], v[162:165], v[94:97]
	s_waitcnt lgkmcnt(1)
	v_mfma_f32_16x16x32_bf16 v[38:41], v[234:237], v[162:165], v[38:41]
	s_waitcnt lgkmcnt(0)
	v_mfma_f32_16x16x32_bf16 v[90:93], v[140:143], v[162:165], v[90:93]
	v_mfma_f32_16x16x32_bf16 v[42:45], v[226:229], v[198:201], v[42:45]
	v_mfma_f32_16x16x32_bf16 v[86:89], v[132:135], v[198:201], v[86:89]
	v_mfma_f32_16x16x32_bf16 v[46:49], v[234:237], v[198:201], v[46:49]
	v_mfma_f32_16x16x32_bf16 v[82:85], v[140:143], v[198:201], v[82:85]
	v_mfma_f32_16x16x32_bf16 v[50:53], v[226:229], v[206:209], v[50:53]
	v_mfma_f32_16x16x32_bf16 v[78:81], v[132:135], v[206:209], v[78:81]
	v_mfma_f32_16x16x32_bf16 v[54:57], v[234:237], v[206:209], v[54:57]
	v_mfma_f32_16x16x32_bf16 v[70:73], v[140:143], v[206:209], v[70:73]
	v_mfma_f32_16x16x32_bf16 v[58:61], v[226:229], v[214:217], v[58:61]
	v_mfma_f32_16x16x32_bf16 v[66:69], v[132:135], v[214:217], v[66:69]
	v_mfma_f32_16x16x32_bf16 v[62:65], v[234:237], v[214:217], v[62:65]
	v_mfma_f32_16x16x32_bf16 v[74:77], v[140:143], v[214:217], v[74:77]
	s_waitcnt vmcnt(0)
	s_setprio 0
	s_add_i32 s5, s5, 2
	s_add_u32 s38, s38, 0x100
	s_addc_u32 s39, s39, 0
	s_cmp_lt_u32 s5, 10
	s_waitcnt lgkmcnt(0)
	s_barrier
	s_cbranch_scc1 .Lk3_mid_157
	s_setprio 1
	s_add_u32 s98, s38, s36
	s_addc_u32 s99, s39, 0
	s_add_u32 s98, s98, 0x80
	s_addc_u32 s99, s99, 0
	v_add_u32_e32 v122, v119, v118
	v_add_u32_e32 v124, v119, v120
	v_add_u32_e32 v123, v121, v120
	ds_read_b128 v[126:129], v122 offset:16384
	ds_read_b128 v[144:147], v122 offset:18432
	ds_read_b128 v[158:161], v122 offset:20480
	ds_read_b128 v[162:165], v122 offset:22528
	ds_read_b128 v[130:133], v124
	ds_read_b128 v[134:137], v124 offset:2048
	ds_read_b128 v[140:143], v124 offset:4096
	ds_read_b128 v[148:151], v124 offset:6144
	s_add_u32 m0, s100, 0x8000
	s_waitcnt lgkmcnt(3)
	v_mfma_f32_16x16x32_bf16 v[34:37], v[126:129], v[130:133], v[34:37]
	global_load_lds_dwordx4 v194, s[98:99]
	v_mfma_f32_16x16x32_bf16 v[94:97], v[144:147], v[130:133], v[94:97]
	ds_read_b128 v[198:201], v123
	s_add_u32 m0, s100, 0xc000
	v_mfma_f32_16x16x32_bf16 v[38:41], v[158:161], v[130:133], v[38:41]
	global_load_lds_dwordx4 v195, s[98:99]
	v_mfma_f32_16x16x32_bf16 v[90:93], v[162:165], v[130:133], v[90:93]
	ds_read_b128 v[206:209], v123 offset:2048
	s_add_u32 m0, s100, 0x9000
	s_waitcnt lgkmcnt(4)
	v_mfma_f32_16x16x32_bf16 v[42:45], v[126:129], v[134:137], v[42:45]
	global_load_lds_dwordx4 v196, s[98:99]
	v_mfma_f32_16x16x32_bf16 v[86:89], v[144:147], v[134:137], v[86:89]
	ds_read_b128 v[214:217], v123 offset:4096
	s_add_u32 m0, s100, 0xd000
	v_mfma_f32_16x16x32_bf16 v[46:49], v[158:161], v[134:137], v[46:49]
	global_load_lds_dwordx4 v197, s[98:99]
	v_mfma_f32_16x16x32_bf16 v[82:85], v[162:165], v[134:137], v[82:85]
	v_add_u32_e32 v130, v121, v118
	ds_read_b128 v[132:135], v123 offset:6144
	s_add_u32 m0, s100, 0xa000
	s_waitcnt lgkmcnt(5)
	v_mfma_f32_16x16x32_bf16 v[50:53], v[126:129], v[140:143], v[50:53]
	global_load_lds_dwordx4 v202, s[98:99]
	v_mfma_f32_16x16x32_bf16 v[78:81], v[144:147], v[140:143], v[78:81]
	ds_read_b128 v[226:229], v130 offset:16384
	s_add_u32 m0, s100, 0xe000
	v_mfma_f32_16x16x32_bf16 v[54:57], v[158:161], v[140:143], v[54:57]
	global_load_lds_dwordx4 v203, s[98:99]
	v_mfma_f32_16x16x32_bf16 v[70:73], v[162:165], v[140:143], v[70:73]
	ds_read_b128 v[140:143], v130 offset:18432
	s_add_u32 m0, s100, 0xb000
	s_waitcnt lgkmcnt(6)
	v_mfma_f32_16x16x32_bf16 v[58:61], v[126:129], v[148:151], v[58:61]
	global_load_lds_dwordx4 v204, s[98:99]
	v_mfma_f32_16x16x32_bf16 v[66:69], v[144:147], v[148:151], v[66:69]
	ds_read_b128 v[144:147], v130 offset:20480
	s_add_u32 m0, s100, 0xf000
	v_mfma_f32_16x16x32_bf16 v[62:65], v[158:161], v[148:151], v[62:65]
	global_load_lds_dwordx4 v205, s[98:99]
	v_mfma_f32_16x16x32_bf16 v[74:77], v[162:165], v[148:151], v[74:77]
	ds_read_b128 v[148:151], v130 offset:22528
	s_waitcnt lgkmcnt(3)
	v_mfma_f32_16x16x32_bf16 v[34:37], v[226:229], v[198:201], v[34:37]
	s_waitcnt lgkmcnt(2)
	v_mfma_f32_16x16x32_bf16 v[94:97], v[140:143], v[198:201], v[94:97]
	s_waitcnt lgkmcnt(1)
	v_mfma_f32_16x16x32_bf16 v[38:41], v[144:147], v[198:201], v[38:41]
	s_waitcnt lgkmcnt(0)
	v_mfma_f32_16x16x32_bf16 v[90:93], v[148:151], v[198:201], v[90:93]
	v_mfma_f32_16x16x32_bf16 v[42:45], v[226:229], v[206:209], v[42:45]
	v_mfma_f32_16x16x32_bf16 v[86:89], v[140:143], v[206:209], v[86:89]
	v_mfma_f32_16x16x32_bf16 v[46:49], v[144:147], v[206:209], v[46:49]
	v_mfma_f32_16x16x32_bf16 v[82:85], v[148:151], v[206:209], v[82:85]
	v_mfma_f32_16x16x32_bf16 v[50:53], v[226:229], v[214:217], v[50:53]
	v_mfma_f32_16x16x32_bf16 v[78:81], v[140:143], v[214:217], v[78:81]
	v_mfma_f32_16x16x32_bf16 v[54:57], v[144:147], v[214:217], v[54:57]
	v_mfma_f32_16x16x32_bf16 v[70:73], v[148:151], v[214:217], v[70:73]
	v_mfma_f32_16x16x32_bf16 v[58:61], v[226:229], v[132:135], v[58:61]
	v_mfma_f32_16x16x32_bf16 v[66:69], v[140:143], v[132:135], v[66:69]
	v_mfma_f32_16x16x32_bf16 v[62:65], v[144:147], v[132:135], v[62:65]
	v_mfma_f32_16x16x32_bf16 v[74:77], v[148:151], v[132:135], v[74:77]
	s_waitcnt vmcnt(0)
	s_setprio 0
	s_waitcnt lgkmcnt(0)
	s_barrier
	s_setprio 1
	s_add_u32 s98, s98, 0x80
	s_addc_u32 s99, s99, 0
	ds_read_b128 v[26:29], v122 offset:49152
	ds_read_b128 v[30:33], v122 offset:51200
	ds_read_b128 v[144:147], v122 offset:53248
	ds_read_b128 v[148:151], v122 offset:55296
	ds_read_b128 v[10:13], v124 offset:32768
	ds_read_b128 v[18:21], v124 offset:34816
	ds_read_b128 v[132:135], v124 offset:36864
	ds_read_b128 v[140:143], v124 offset:38912
	s_add_u32 m0, s100, 0x0
	s_waitcnt lgkmcnt(3)
	v_mfma_f32_16x16x32_bf16 v[34:37], v[26:29], v[10:13], v[34:37]
	global_load_lds_dwordx4 v194, s[98:99]
	v_mfma_f32_16x16x32_bf16 v[94:97], v[30:33], v[10:13], v[94:97]
	ds_read_b128 v[162:165], v123 offset:32768
	s_add_u32 m0, s100, 0x4000
	v_mfma_f32_16x16x32_bf16 v[38:41], v[144:147], v[10:13], v[38:41]
	global_load_lds_dwordx4 v195, s[98:99]
	v_mfma_f32_16x16x32_bf16 v[90:93], v[148:151], v[10:13], v[90:93]
	ds_read_b128 v[198:201], v123 offset:34816
	s_add_u32 m0, s100, 0x1000
	s_waitcnt lgkmcnt(4)
	v_mfma_f32_16x16x32_bf16 v[42:45], v[26:29], v[18:21], v[42:45]
	global_load_lds_dwordx4 v196, s[98:99]
	v_mfma_f32_16x16x32_bf16 v[86:89], v[30:33], v[18:21], v[86:89]
	ds_read_b128 v[206:209], v123 offset:36864
	s_add_u32 m0, s100, 0x5000
	v_mfma_f32_16x16x32_bf16 v[46:49], v[144:147], v[18:21], v[46:49]
	global_load_lds_dwordx4 v197, s[98:99]
	v_mfma_f32_16x16x32_bf16 v[82:85], v[148:151], v[18:21], v[82:85]
	ds_read_b128 v[214:217], v123 offset:38912
	s_add_u32 m0, s100, 0x2000
	s_waitcnt lgkmcnt(5)
	v_mfma_f32_16x16x32_bf16 v[50:53], v[26:29], v[132:135], v[50:53]
	global_load_lds_dwordx4 v202, s[98:99]
	v_mfma_f32_16x16x32_bf16 v[78:81], v[30:33], v[132:135], v[78:81]
	ds_read_b128 v[226:229], v130 offset:49152
	s_add_u32 m0, s100, 0x6000
	v_mfma_f32_16x16x32_bf16 v[54:57], v[144:147], v[132:135], v[54:57]
	global_load_lds_dwordx4 v203, s[98:99]
	v_mfma_f32_16x16x32_bf16 v[70:73], v[148:151], v[132:135], v[70:73]
	ds_read_b128 v[132:135], v130 offset:51200
	s_add_u32 m0, s100, 0x3000
	s_waitcnt lgkmcnt(6)
	v_mfma_f32_16x16x32_bf16 v[58:61], v[26:29], v[140:143], v[58:61]
	global_load_lds_dwordx4 v204, s[98:99]
	v_mfma_f32_16x16x32_bf16 v[66:69], v[30:33], v[140:143], v[66:69]
	ds_read_b128 v[234:237], v130 offset:53248
	s_add_u32 m0, s100, 0x7000
	v_mfma_f32_16x16x32_bf16 v[62:65], v[144:147], v[140:143], v[62:65]
	global_load_lds_dwordx4 v205, s[98:99]
	v_mfma_f32_16x16x32_bf16 v[74:77], v[148:151], v[140:143], v[74:77]
	ds_read_b128 v[140:143], v130 offset:55296
	s_waitcnt lgkmcnt(3)
	v_mfma_f32_16x16x32_bf16 v[34:37], v[226:229], v[162:165], v[34:37]
	global_load_dwordx4 v[2:5], v210, s[98:99] offset:128
	s_waitcnt lgkmcnt(2)
	v_mfma_f32_16x16x32_bf16 v[94:97], v[132:135], v[162:165], v[94:97]
	s_waitcnt lgkmcnt(1)
	v_mfma_f32_16x16x32_bf16 v[38:41], v[234:237], v[162:165], v[38:41]
	global_load_dwordx4 v[6:9], v211, s[98:99] offset:128
	s_waitcnt lgkmcnt(0)
	v_mfma_f32_16x16x32_bf16 v[90:93], v[140:143], v[162:165], v[90:93]
	v_mfma_f32_16x16x32_bf16 v[42:45], v[226:229], v[198:201], v[42:45]
	global_load_dwordx4 v[10:13], v212, s[98:99] offset:128
	v_mfma_f32_16x16x32_bf16 v[86:89], v[132:135], v[198:201], v[86:89]
	v_mfma_f32_16x16x32_bf16 v[46:49], v[234:237], v[198:201], v[46:49]
	global_load_dwordx4 v[14:17], v213, s[98:99] offset:128
	v_mfma_f32_16x16x32_bf16 v[82:85], v[140:143], v[198:201], v[82:85]
	v_mfma_f32_16x16x32_bf16 v[50:53], v[226:229], v[206:209], v[50:53]
	global_load_dwordx4 v[18:21], v218, s[98:99] offset:128
	v_mfma_f32_16x16x32_bf16 v[78:81], v[132:135], v[206:209], v[78:81]
	v_mfma_f32_16x16x32_bf16 v[54:57], v[234:237], v[206:209], v[54:57]
	global_load_dwordx4 v[22:25], v219, s[98:99] offset:128
	v_mfma_f32_16x16x32_bf16 v[70:73], v[140:143], v[206:209], v[70:73]
	v_mfma_f32_16x16x32_bf16 v[58:61], v[226:229], v[214:217], v[58:61]
	global_load_dwordx4 v[26:29], v220, s[98:99] offset:128
	v_mfma_f32_16x16x32_bf16 v[66:69], v[132:135], v[214:217], v[66:69]
	v_mfma_f32_16x16x32_bf16 v[62:65], v[234:237], v[214:217], v[62:65]
	global_load_dwordx4 v[30:33], v221, s[98:99] offset:128
	v_mfma_f32_16x16x32_bf16 v[74:77], v[140:143], v[214:217], v[74:77]
	s_waitcnt vmcnt(8)
	s_setprio 0
	s_add_i32 s5, s5, 2
	s_add_u32 s38, s38, 0x100
	s_addc_u32 s39, s39, 0
	s_waitcnt lgkmcnt(0)
	s_barrier
	s_add_i32 s5, s11, s2
	s_cmpk_lt_u32 s5, 0x100
	s_cselect_b64 s[44:45], -1, 0
	s_and_b64 s[8:9], s[44:45], exec
	s_cselect_b32 s9, s5, s11
	s_lshr_b32 s8, s9, 3
	s_and_b32 s8, s8, 0x1fffff8
	s_add_i32 s8, s8, s21
	s_and_b32 s11, s9, 7
	v_mov_b32_e32 v0, v169
	s_or_b32 s8, s8, s11
	s_lshl_b32 s8, s8, 7
	v_lshrrev_b32_e32 v98, 3, v0
	v_lshlrev_b32_e32 v0, 3, v0
	v_add_u32_e32 v98, s8, v98
	v_and_b32_e32 v0, 56, v0
	v_lshl_or_b32 v0, v98, 10, v0
	v_mov_b32_e32 v98, v169
	s_lshl_b32 s9, s9, 4
	s_and_b32 s9, s9, 0x380
	v_lshrrev_b32_e32 v99, 3, v98
	v_lshlrev_b32_e32 v98, 3, v98
	v_add_u32_e32 v99, s9, v99
	v_and_b32_e32 v98, 56, v98
	v_add_u32_e32 v114, 0x8000, v0
	v_add_u32_e32 v136, 0x10000, v0
	v_lshl_or_b32 v162, v99, 10, v98
	v_add_u32_e32 v166, 0x18000, v0
	v_add_u32_e32 v174, 0x8000, v162
	v_add_u32_e32 v176, 0x10000, v162
	v_add_u32_e32 v178, 0x18000, v162
	s_setprio 1
	ds_read_b128 v[98:101], v122 offset:16384
	ds_read_b128 v[110:113], v122 offset:18432
	ds_read_b128 v[132:135], v122 offset:20480
	ds_read_b128 v[140:143], v122 offset:22528
	ds_read_b128 v[102:105], v124
	ds_read_b128 v[106:109], v124 offset:2048
	ds_read_b128 v[118:121], v124 offset:4096
	ds_read_b128 v[126:129], v124 offset:6144
	v_readlane_b32 s14, v254, 45
	v_readlane_b32 s15, v254, 46
	v_mov_b32_e32 v163, v1
	v_mov_b32_e32 v115, v1
	v_mov_b32_e32 v175, v1
	v_mov_b32_e32 v137, v1
	v_mov_b32_e32 v177, v1
	v_mov_b32_e32 v167, v1
	v_mov_b32_e32 v179, v1
	v_lshl_add_u64 v[180:181], v[0:1], 1, s[14:15]
	v_lshl_add_u64 v[186:187], v[162:163], 1, s[34:35]
	v_lshl_add_u64 v[188:189], v[114:115], 1, s[14:15]
	v_lshl_add_u64 v[174:175], v[174:175], 1, s[34:35]
	v_lshl_add_u64 v[136:137], v[136:137], 1, s[14:15]
	v_lshl_add_u64 v[176:177], v[176:177], 1, s[34:35]
	v_lshl_add_u64 v[166:167], v[166:167], 1, s[14:15]
	v_lshl_add_u64 v[178:179], v[178:179], 1, s[34:35]
	s_waitcnt lgkmcnt(3)
	v_mfma_f32_16x16x32_bf16 v[144:147], v[98:101], v[102:105], v[34:37]
	s_nop 2
	global_load_dwordx4 v[34:37], v[180:181], off
	v_mfma_f32_16x16x32_bf16 v[94:97], v[110:113], v[102:105], v[94:97]
	ds_read_b128 v[148:151], v123
	v_mfma_f32_16x16x32_bf16 v[158:161], v[132:135], v[102:105], v[38:41]
	s_nop 2
	global_load_dwordx4 v[38:41], v[186:187], off
	v_mfma_f32_16x16x32_bf16 v[90:93], v[140:143], v[102:105], v[90:93]
	ds_read_b128 v[102:105], v123 offset:2048
	s_waitcnt lgkmcnt(4)
	v_mfma_f32_16x16x32_bf16 v[162:165], v[98:101], v[106:109], v[42:45]
	s_nop 2
	global_load_dwordx4 v[42:45], v[188:189], off
	v_mfma_f32_16x16x32_bf16 v[86:89], v[110:113], v[106:109], v[86:89]
	ds_read_b128 v[194:197], v123 offset:4096
	v_mfma_f32_16x16x32_bf16 v[198:201], v[132:135], v[106:109], v[46:49]
	s_nop 2
	global_load_dwordx4 v[46:49], v[174:175], off
	v_mfma_f32_16x16x32_bf16 v[82:85], v[140:143], v[106:109], v[82:85]
	ds_read_b128 v[106:109], v123 offset:6144
	s_waitcnt lgkmcnt(5)
	v_mfma_f32_16x16x32_bf16 v[202:205], v[98:101], v[118:121], v[50:53]
	s_nop 2
	global_load_dwordx4 v[50:53], v[136:137], off
	v_mfma_f32_16x16x32_bf16 v[78:81], v[110:113], v[118:121], v[78:81]
	ds_read_b128 v[206:209], v130 offset:16384
	v_mfma_f32_16x16x32_bf16 v[210:213], v[132:135], v[118:121], v[54:57]
	s_nop 2
	global_load_dwordx4 v[54:57], v[176:177], off
	v_mfma_f32_16x16x32_bf16 v[70:73], v[140:143], v[118:121], v[70:73]
	ds_read_b128 v[118:121], v130 offset:18432
	s_waitcnt lgkmcnt(6)
	v_mfma_f32_16x16x32_bf16 v[98:101], v[98:101], v[126:129], v[58:61]
	s_nop 2
	global_load_dwordx4 v[58:61], v[166:167], off
	v_mfma_f32_16x16x32_bf16 v[66:69], v[110:113], v[126:129], v[66:69]
	ds_read_b128 v[110:113], v130 offset:20480
	v_mfma_f32_16x16x32_bf16 v[132:135], v[132:135], v[126:129], v[62:65]
	s_nop 2
	global_load_dwordx4 v[62:65], v[178:179], off
	v_mfma_f32_16x16x32_bf16 v[74:77], v[140:143], v[126:129], v[74:77]
	ds_read_b128 v[126:129], v130 offset:22528
	s_waitcnt lgkmcnt(3)
	v_mfma_f32_16x16x32_bf16 v[140:143], v[206:209], v[148:151], v[144:147]
	s_waitcnt vmcnt(15)
	ds_write_b128 v117, v[2:5] offset:32768
	s_waitcnt lgkmcnt(3)
	v_mfma_f32_16x16x32_bf16 v[94:97], v[118:121], v[148:151], v[94:97]
	s_waitcnt lgkmcnt(2)
	v_mfma_f32_16x16x32_bf16 v[144:147], v[110:113], v[148:151], v[158:161]
	s_waitcnt vmcnt(14)
	ds_write_b128 v116, v[6:9] offset:49152
	s_waitcnt lgkmcnt(2)
	v_mfma_f32_16x16x32_bf16 v[90:93], v[126:129], v[148:151], v[90:93]
	v_mfma_f32_16x16x32_bf16 v[148:151], v[206:209], v[102:105], v[162:165]
	s_waitcnt vmcnt(13)
	ds_write_b128 v117, v[10:13] offset:36864
	v_mfma_f32_16x16x32_bf16 v[86:89], v[118:121], v[102:105], v[86:89]
	v_mfma_f32_16x16x32_bf16 v[158:161], v[110:113], v[102:105], v[198:201]
	s_waitcnt vmcnt(12)
	ds_write_b128 v116, v[14:17] offset:53248
	v_mfma_f32_16x16x32_bf16 v[82:85], v[126:129], v[102:105], v[82:85]
	v_mfma_f32_16x16x32_bf16 v[102:105], v[206:209], v[194:197], v[202:205]
	s_waitcnt vmcnt(11)
	ds_write_b128 v117, v[18:21] offset:40960
	v_mfma_f32_16x16x32_bf16 v[78:81], v[118:121], v[194:197], v[78:81]
	v_mfma_f32_16x16x32_bf16 v[162:165], v[110:113], v[194:197], v[210:213]
	s_waitcnt vmcnt(10)
	ds_write_b128 v116, v[22:25] offset:57344
	v_mfma_f32_16x16x32_bf16 v[70:73], v[126:129], v[194:197], v[70:73]
	v_mfma_f32_16x16x32_bf16 v[98:101], v[206:209], v[106:109], v[98:101]
	s_waitcnt vmcnt(9)
	ds_write_b128 v117, v[26:29] offset:45056
	v_mfma_f32_16x16x32_bf16 v[66:69], v[118:121], v[106:109], v[66:69]
	v_mfma_f32_16x16x32_bf16 v[110:113], v[110:113], v[106:109], v[132:135]
	s_waitcnt vmcnt(8)
	ds_write_b128 v116, v[30:33] offset:61440
	v_mfma_f32_16x16x32_bf16 v[74:77], v[126:129], v[106:109], v[74:77]
	s_setprio 0
	s_waitcnt lgkmcnt(0)
	s_barrier
	s_setprio 1
	ds_read_b128 v[26:29], v122 offset:49152
	ds_read_b128 v[10:13], v124 offset:32768
	ds_read_b128 v[18:21], v124 offset:34816
	ds_read_b128 v[30:33], v122 offset:51200
	ds_read_b128 v[106:109], v124 offset:36864
	ds_read_b128 v[114:117], v124 offset:38912
	ds_read_b128 v[118:121], v122 offset:53248
	ds_read_b128 v[124:127], v122 offset:55296
	s_waitcnt lgkmcnt(6)
	v_mfma_f32_16x16x32_bf16 v[132:135], v[26:29], v[10:13], v[140:143]
	global_load_dwordx4 v[2:5], v[180:181], off offset:128
	s_waitcnt lgkmcnt(4)
	v_mfma_f32_16x16x32_bf16 v[94:97], v[30:33], v[10:13], v[94:97]
	ds_read_b128 v[140:143], v123 offset:32768
	s_waitcnt lgkmcnt(2)
	v_mfma_f32_16x16x32_bf16 v[144:147], v[118:121], v[10:13], v[144:147]
	global_load_dwordx4 v[6:9], v[186:187], off offset:128
	s_waitcnt lgkmcnt(1)
	v_mfma_f32_16x16x32_bf16 v[90:93], v[124:127], v[10:13], v[90:93]
	ds_read_b128 v[194:197], v123 offset:34816
	v_mfma_f32_16x16x32_bf16 v[148:151], v[26:29], v[18:21], v[148:151]
	global_load_dwordx4 v[10:13], v[188:189], off offset:128
	v_mfma_f32_16x16x32_bf16 v[86:89], v[30:33], v[18:21], v[86:89]
	ds_read_b128 v[198:201], v123 offset:36864
	v_mfma_f32_16x16x32_bf16 v[158:161], v[118:121], v[18:21], v[158:161]
	global_load_dwordx4 v[14:17], v[174:175], off offset:128
	v_mfma_f32_16x16x32_bf16 v[82:85], v[124:127], v[18:21], v[82:85]
	ds_read_b128 v[202:205], v123 offset:38912
	v_mfma_f32_16x16x32_bf16 v[206:209], v[26:29], v[106:109], v[102:105]
	global_load_dwordx4 v[18:21], v[136:137], off offset:128
	v_mfma_f32_16x16x32_bf16 v[78:81], v[30:33], v[106:109], v[78:81]
	ds_read_b128 v[210:213], v130 offset:49152
	v_mfma_f32_16x16x32_bf16 v[162:165], v[118:121], v[106:109], v[162:165]
	global_load_dwordx4 v[22:25], v[176:177], off offset:128
	v_mfma_f32_16x16x32_bf16 v[70:73], v[124:127], v[106:109], v[70:73]
	ds_read_b128 v[214:217], v130 offset:51200
	v_mfma_f32_16x16x32_bf16 v[218:221], v[26:29], v[114:117], v[98:101]
	global_load_dwordx4 v[26:29], v[166:167], off offset:128
	v_mfma_f32_16x16x32_bf16 v[66:69], v[30:33], v[114:117], v[66:69]
	ds_read_b128 v[222:225], v130 offset:53248
	v_mfma_f32_16x16x32_bf16 v[226:229], v[118:121], v[114:117], v[110:113]
	global_load_dwordx4 v[30:33], v[178:179], off offset:128
	v_mfma_f32_16x16x32_bf16 v[230:233], v[124:127], v[114:117], v[74:77]
	s_waitcnt lgkmcnt(2)
	v_mfma_f32_16x16x32_bf16 v[126:129], v[210:213], v[140:143], v[132:135]
	s_nop 2
	ds_read_b128 v[130:133], v130 offset:55296
	s_waitcnt lgkmcnt(2)
	v_mfma_f32_16x16x32_bf16 v[122:125], v[214:217], v[140:143], v[94:97]
	s_waitcnt lgkmcnt(1)
	v_mfma_f32_16x16x32_bf16 v[118:121], v[222:225], v[140:143], v[144:147]
	s_waitcnt lgkmcnt(0)
	v_mfma_f32_16x16x32_bf16 v[114:117], v[130:133], v[140:143], v[90:93]
	v_mfma_f32_16x16x32_bf16 v[110:113], v[210:213], v[194:197], v[148:151]
	v_mfma_f32_16x16x32_bf16 v[106:109], v[214:217], v[194:197], v[86:89]
	v_mfma_f32_16x16x32_bf16 v[102:105], v[222:225], v[194:197], v[158:161]
	v_mfma_f32_16x16x32_bf16 v[98:101], v[130:133], v[194:197], v[82:85]
	v_mfma_f32_16x16x32_bf16 v[94:97], v[210:213], v[198:201], v[206:209]
	v_mfma_f32_16x16x32_bf16 v[90:93], v[214:217], v[198:201], v[78:81]
	v_mfma_f32_16x16x32_bf16 v[86:89], v[222:225], v[198:201], v[162:165]
	v_mfma_f32_16x16x32_bf16 v[82:85], v[130:133], v[198:201], v[70:73]
	v_mfma_f32_16x16x32_bf16 v[78:81], v[210:213], v[202:205], v[218:221]
	v_mfma_f32_16x16x32_bf16 v[74:77], v[214:217], v[202:205], v[66:69]
	v_mfma_f32_16x16x32_bf16 v[70:73], v[222:225], v[202:205], v[226:229]
	v_mfma_f32_16x16x32_bf16 v[66:69], v[130:133], v[202:205], v[230:233]
	s_setprio 0
	v_add_u32_e32 v134, s4, v152
	v_ashrrev_i32_e32 v135, 31, v134
	v_lshlrev_b64 v[136:137], 12, v[134:135]
	v_or_b32_e32 v140, s10, v153
	v_mov_b32_e32 v141, v1
	v_cndmask_b32_e64 v0, 0, 1, s[42:43]
	v_lshl_add_u64 v[130:131], s[40:41], 0, v[136:137]
	v_cmp_ne_u32_e64 s[38:39], 1, v0
	s_andn2_b64 vcc, exec, s[42:43]
	v_lshl_add_u64 v[146:147], v[140:141], 2, v[130:131]
	s_barrier
	v_readlane_b32 s48, v253, 18
	v_readlane_b32 s49, v253, 19
	v_readlane_b32 s50, v253, 20
	v_readlane_b32 s51, v253, 21
	v_readlane_b32 s52, v253, 22
	v_readlane_b32 s53, v253, 23
	v_readlane_b32 s54, v253, 24
	v_readlane_b32 s55, v253, 25
	v_readlane_b32 s56, v253, 26
	v_readlane_b32 s57, v253, 27
	v_readlane_b32 s58, v253, 28
	v_readlane_b32 s59, v253, 29
	v_readlane_b32 s60, v253, 30
	v_readlane_b32 s61, v253, 31
	v_readlane_b32 s62, v253, 32
	v_readlane_b32 s63, v253, 33
	v_or_b32_e32 v0, s10, v153
	v_lshlrev_b32_e32 v0, 2, v0
	v_add_u32_e32 v130, s4, v152
	v_lshlrev_b32_e32 v158, 3, v130
	v_lshlrev_b32_e32 v130, 12, v130
	v_add_u32_e32 v130, v130, v0
	v_add_u32_e32 v131, s4, v154
	v_lshlrev_b32_e32 v162, 3, v131
	v_lshlrev_b32_e32 v131, 12, v131
	v_add_u32_e32 v131, v131, v0
	v_add_u32_e32 v132, s4, v155
	v_lshlrev_b32_e32 v234, 3, v132
	v_lshlrev_b32_e32 v132, 12, v132
	v_add_u32_e32 v132, v132, v0
	v_add_u32_e32 v133, s4, v156
	v_lshlrev_b32_e32 v238, 3, v133
	v_lshlrev_b32_e32 v133, 12, v133
	v_add_u32_e32 v133, v133, v0
	s_mov_b32 s10, 0x3fb504f3
	s_cmp_lg_u64 s[40:41], 0
	s_cbranch_scc0 .Lepi_ln_157
	global_load_dwordx4 v[158:161], v130, s[40:41]
	global_load_dwordx4 v[162:165], v131, s[40:41]
	global_load_dwordx4 v[234:237], v132, s[40:41]
	global_load_dwordx4 v[238:241], v133, s[40:41]
	s_waitcnt vmcnt(3)
	v_pk_fma_f32 v[126:127], v[158:159], s[10:11], v[126:127] op_sel_hi:[1,0,1]
	v_pk_fma_f32 v[128:129], v[160:161], s[10:11], v[128:129] op_sel_hi:[1,0,1]
	global_store_dwordx4 v130, v[126:129], s[62:63]
	s_waitcnt vmcnt(3)
	v_pk_fma_f32 v[110:111], v[162:163], s[10:11], v[110:111] op_sel_hi:[1,0,1]
	v_pk_fma_f32 v[112:113], v[164:165], s[10:11], v[112:113] op_sel_hi:[1,0,1]
	global_store_dwordx4 v131, v[110:113], s[62:63]
	s_waitcnt vmcnt(3)
	v_pk_fma_f32 v[94:95], v[234:235], s[10:11], v[94:95] op_sel_hi:[1,0,1]
	v_pk_fma_f32 v[96:97], v[236:237], s[10:11], v[96:97] op_sel_hi:[1,0,1]
	global_store_dwordx4 v132, v[94:97], s[62:63]
	s_waitcnt vmcnt(3)
	v_pk_fma_f32 v[78:79], v[238:239], s[10:11], v[78:79] op_sel_hi:[1,0,1]
	v_pk_fma_f32 v[80:81], v[240:241], s[10:11], v[80:81] op_sel_hi:[1,0,1]
	global_store_dwordx4 v133, v[78:81], s[62:63]
	global_load_dwordx4 v[158:161], v130, s[40:41] offset:16
	global_load_dwordx4 v[162:165], v131, s[40:41] offset:16
	global_load_dwordx4 v[234:237], v132, s[40:41] offset:16
	global_load_dwordx4 v[238:241], v133, s[40:41] offset:16
	s_waitcnt vmcnt(3)
	v_pk_fma_f32 v[122:123], v[158:159], s[10:11], v[122:123] op_sel_hi:[1,0,1]
	v_pk_fma_f32 v[124:125], v[160:161], s[10:11], v[124:125] op_sel_hi:[1,0,1]
	global_store_dwordx4 v130, v[122:125], s[62:63] offset:16
	s_waitcnt vmcnt(3)
	v_pk_fma_f32 v[106:107], v[162:163], s[10:11], v[106:107] op_sel_hi:[1,0,1]
	v_pk_fma_f32 v[108:109], v[164:165], s[10:11], v[108:109] op_sel_hi:[1,0,1]
	global_store_dwordx4 v131, v[106:109], s[62:63] offset:16
	s_waitcnt vmcnt(3)
	v_pk_fma_f32 v[90:91], v[234:235], s[10:11], v[90:91] op_sel_hi:[1,0,1]
	v_pk_fma_f32 v[92:93], v[236:237], s[10:11], v[92:93] op_sel_hi:[1,0,1]
	global_store_dwordx4 v132, v[90:93], s[62:63] offset:16
	s_waitcnt vmcnt(3)
	v_pk_fma_f32 v[74:75], v[238:239], s[10:11], v[74:75] op_sel_hi:[1,0,1]
	v_pk_fma_f32 v[76:77], v[240:241], s[10:11], v[76:77] op_sel_hi:[1,0,1]
	global_store_dwordx4 v133, v[74:77], s[62:63] offset:16
	global_load_dwordx4 v[158:161], v130, s[40:41] offset:128
	global_load_dwordx4 v[162:165], v131, s[40:41] offset:128
	global_load_dwordx4 v[234:237], v132, s[40:41] offset:128
	global_load_dwordx4 v[238:241], v133, s[40:41] offset:128
	s_waitcnt vmcnt(3)
	v_pk_fma_f32 v[118:119], v[158:159], s[10:11], v[118:119] op_sel_hi:[1,0,1]
	v_pk_fma_f32 v[120:121], v[160:161], s[10:11], v[120:121] op_sel_hi:[1,0,1]
	global_store_dwordx4 v130, v[118:121], s[62:63] offset:128
	s_waitcnt vmcnt(3)
	v_pk_fma_f32 v[102:103], v[162:163], s[10:11], v[102:103] op_sel_hi:[1,0,1]
	v_pk_fma_f32 v[104:105], v[164:165], s[10:11], v[104:105] op_sel_hi:[1,0,1]
	global_store_dwordx4 v131, v[102:105], s[62:63] offset:128
	s_waitcnt vmcnt(3)
	v_pk_fma_f32 v[86:87], v[234:235], s[10:11], v[86:87] op_sel_hi:[1,0,1]
	v_pk_fma_f32 v[88:89], v[236:237], s[10:11], v[88:89] op_sel_hi:[1,0,1]
	global_store_dwordx4 v132, v[86:89], s[62:63] offset:128
	s_waitcnt vmcnt(3)
	v_pk_fma_f32 v[70:71], v[238:239], s[10:11], v[70:71] op_sel_hi:[1,0,1]
	v_pk_fma_f32 v[72:73], v[240:241], s[10:11], v[72:73] op_sel_hi:[1,0,1]
	global_store_dwordx4 v133, v[70:73], s[62:63] offset:128
	global_load_dwordx4 v[158:161], v130, s[40:41] offset:144
	global_load_dwordx4 v[162:165], v131, s[40:41] offset:144
	global_load_dwordx4 v[234:237], v132, s[40:41] offset:144
	global_load_dwordx4 v[238:241], v133, s[40:41] offset:144
	s_waitcnt vmcnt(3)
	v_pk_fma_f32 v[114:115], v[158:159], s[10:11], v[114:115] op_sel_hi:[1,0,1]
	v_pk_fma_f32 v[116:117], v[160:161], s[10:11], v[116:117] op_sel_hi:[1,0,1]
	global_store_dwordx4 v130, v[114:117], s[62:63] offset:144
	s_waitcnt vmcnt(3)
	v_pk_fma_f32 v[98:99], v[162:163], s[10:11], v[98:99] op_sel_hi:[1,0,1]
	v_pk_fma_f32 v[100:101], v[164:165], s[10:11], v[100:101] op_sel_hi:[1,0,1]
	global_store_dwordx4 v131, v[98:101], s[62:63] offset:144
	s_waitcnt vmcnt(3)
	v_pk_fma_f32 v[82:83], v[234:235], s[10:11], v[82:83] op_sel_hi:[1,0,1]
	v_pk_fma_f32 v[84:85], v[236:237], s[10:11], v[84:85] op_sel_hi:[1,0,1]
	global_store_dwordx4 v132, v[82:85], s[62:63] offset:144
	s_waitcnt vmcnt(3)
	v_pk_fma_f32 v[66:67], v[238:239], s[10:11], v[66:67] op_sel_hi:[1,0,1]
	v_pk_fma_f32 v[68:69], v[240:241], s[10:11], v[68:69] op_sel_hi:[1,0,1]
	global_store_dwordx4 v133, v[66:69], s[62:63] offset:144
	s_branch .Lepi_done_157
.Lepi_ln_157:
	global_load_dwordx2 v[134:135], v158, s[0:1]
	global_load_dwordx2 v[136:137], v162, s[0:1]
	global_load_dwordx2 v[140:141], v234, s[0:1]
	global_load_dwordx2 v[142:143], v238, s[0:1]
	global_load_dwordx4 v[144:147], v0, s[58:59]
	global_load_dwordx4 v[148:151], v0, s[60:61]
	global_load_dwordx4 v[158:161], v130, s[62:63]
	global_load_dwordx4 v[162:165], v131, s[62:63]
	global_load_dwordx4 v[234:237], v132, s[62:63]
	global_load_dwordx4 v[238:241], v133, s[62:63]
	s_waitcnt vmcnt(3)
	v_pk_add_f32 v[158:159], v[158:159], v[134:135] op_sel_hi:[1,0] neg_lo:[0,1] neg_hi:[0,1]
	v_pk_add_f32 v[160:161], v[160:161], v[134:135] op_sel_hi:[1,0] neg_lo:[0,1] neg_hi:[0,1]
	v_pk_mul_f32 v[158:159], v[158:159], v[134:135] op_sel:[0,1]
	v_pk_mul_f32 v[160:161], v[160:161], v[134:135] op_sel:[0,1]
	v_pk_fma_f32 v[158:159], v[158:159], v[144:145], v[148:149]
	v_pk_fma_f32 v[160:161], v[160:161], v[146:147], v[150:151]
	v_pk_fma_f32 v[126:127], v[158:159], s[10:11], v[126:127] op_sel_hi:[1,0,1]
	v_pk_fma_f32 v[128:129], v[160:161], s[10:11], v[128:129] op_sel_hi:[1,0,1]
	global_store_dwordx4 v130, v[126:129], s[62:63]
	s_waitcnt vmcnt(3)
	v_pk_add_f32 v[162:163], v[162:163], v[136:137] op_sel_hi:[1,0] neg_lo:[0,1] neg_hi:[0,1]
	v_pk_add_f32 v[164:165], v[164:165], v[136:137] op_sel_hi:[1,0] neg_lo:[0,1] neg_hi:[0,1]
	v_pk_mul_f32 v[162:163], v[162:163], v[136:137] op_sel:[0,1]
	v_pk_mul_f32 v[164:165], v[164:165], v[136:137] op_sel:[0,1]
	v_pk_fma_f32 v[162:163], v[162:163], v[144:145], v[148:149]
	v_pk_fma_f32 v[164:165], v[164:165], v[146:147], v[150:151]
	v_pk_fma_f32 v[110:111], v[162:163], s[10:11], v[110:111] op_sel_hi:[1,0,1]
	v_pk_fma_f32 v[112:113], v[164:165], s[10:11], v[112:113] op_sel_hi:[1,0,1]
	global_store_dwordx4 v131, v[110:113], s[62:63]
	s_waitcnt vmcnt(3)
	v_pk_add_f32 v[234:235], v[234:235], v[140:141] op_sel_hi:[1,0] neg_lo:[0,1] neg_hi:[0,1]
	v_pk_add_f32 v[236:237], v[236:237], v[140:141] op_sel_hi:[1,0] neg_lo:[0,1] neg_hi:[0,1]
	v_pk_mul_f32 v[234:235], v[234:235], v[140:141] op_sel:[0,1]
	v_pk_mul_f32 v[236:237], v[236:237], v[140:141] op_sel:[0,1]
	v_pk_fma_f32 v[234:235], v[234:235], v[144:145], v[148:149]
	v_pk_fma_f32 v[236:237], v[236:237], v[146:147], v[150:151]
	v_pk_fma_f32 v[94:95], v[234:235], s[10:11], v[94:95] op_sel_hi:[1,0,1]
	v_pk_fma_f32 v[96:97], v[236:237], s[10:11], v[96:97] op_sel_hi:[1,0,1]
	global_store_dwordx4 v132, v[94:97], s[62:63]
	s_waitcnt vmcnt(3)
	v_pk_add_f32 v[238:239], v[238:239], v[142:143] op_sel_hi:[1,0] neg_lo:[0,1] neg_hi:[0,1]
	v_pk_add_f32 v[240:241], v[240:241], v[142:143] op_sel_hi:[1,0] neg_lo:[0,1] neg_hi:[0,1]
	v_pk_mul_f32 v[238:239], v[238:239], v[142:143] op_sel:[0,1]
	v_pk_mul_f32 v[240:241], v[240:241], v[142:143] op_sel:[0,1]
	v_pk_fma_f32 v[238:239], v[238:239], v[144:145], v[148:149]
	v_pk_fma_f32 v[240:241], v[240:241], v[146:147], v[150:151]
	v_pk_fma_f32 v[78:79], v[238:239], s[10:11], v[78:79] op_sel_hi:[1,0,1]
	v_pk_fma_f32 v[80:81], v[240:241], s[10:11], v[80:81] op_sel_hi:[1,0,1]
	global_store_dwordx4 v133, v[78:81], s[62:63]
	global_load_dwordx4 v[144:147], v0, s[58:59] offset:16
	global_load_dwordx4 v[148:151], v0, s[60:61] offset:16
	global_load_dwordx4 v[158:161], v130, s[62:63] offset:16
	global_load_dwordx4 v[162:165], v131, s[62:63] offset:16
	global_load_dwordx4 v[234:237], v132, s[62:63] offset:16
	global_load_dwordx4 v[238:241], v133, s[62:63] offset:16
	s_waitcnt vmcnt(3)
	v_pk_add_f32 v[158:159], v[158:159], v[134:135] op_sel_hi:[1,0] neg_lo:[0,1] neg_hi:[0,1]
	v_pk_add_f32 v[160:161], v[160:161], v[134:135] op_sel_hi:[1,0] neg_lo:[0,1] neg_hi:[0,1]
	v_pk_mul_f32 v[158:159], v[158:159], v[134:135] op_sel:[0,1]
	v_pk_mul_f32 v[160:161], v[160:161], v[134:135] op_sel:[0,1]
	v_pk_fma_f32 v[158:159], v[158:159], v[144:145], v[148:149]
	v_pk_fma_f32 v[160:161], v[160:161], v[146:147], v[150:151]
	v_pk_fma_f32 v[122:123], v[158:159], s[10:11], v[122:123] op_sel_hi:[1,0,1]
	v_pk_fma_f32 v[124:125], v[160:161], s[10:11], v[124:125] op_sel_hi:[1,0,1]
	global_store_dwordx4 v130, v[122:125], s[62:63] offset:16
	s_waitcnt vmcnt(3)
	v_pk_add_f32 v[162:163], v[162:163], v[136:137] op_sel_hi:[1,0] neg_lo:[0,1] neg_hi:[0,1]
	v_pk_add_f32 v[164:165], v[164:165], v[136:137] op_sel_hi:[1,0] neg_lo:[0,1] neg_hi:[0,1]
	v_pk_mul_f32 v[162:163], v[162:163], v[136:137] op_sel:[0,1]
	v_pk_mul_f32 v[164:165], v[164:165], v[136:137] op_sel:[0,1]
	v_pk_fma_f32 v[162:163], v[162:163], v[144:145], v[148:149]
	v_pk_fma_f32 v[164:165], v[164:165], v[146:147], v[150:151]
	v_pk_fma_f32 v[106:107], v[162:163], s[10:11], v[106:107] op_sel_hi:[1,0,1]
	v_pk_fma_f32 v[108:109], v[164:165], s[10:11], v[108:109] op_sel_hi:[1,0,1]
	global_store_dwordx4 v131, v[106:109], s[62:63] offset:16
	s_waitcnt vmcnt(3)
	v_pk_add_f32 v[234:235], v[234:235], v[140:141] op_sel_hi:[1,0] neg_lo:[0,1] neg_hi:[0,1]
	v_pk_add_f32 v[236:237], v[236:237], v[140:141] op_sel_hi:[1,0] neg_lo:[0,1] neg_hi:[0,1]
	v_pk_mul_f32 v[234:235], v[234:235], v[140:141] op_sel:[0,1]
	v_pk_mul_f32 v[236:237], v[236:237], v[140:141] op_sel:[0,1]
	v_pk_fma_f32 v[234:235], v[234:235], v[144:145], v[148:149]
	v_pk_fma_f32 v[236:237], v[236:237], v[146:147], v[150:151]
	v_pk_fma_f32 v[90:91], v[234:235], s[10:11], v[90:91] op_sel_hi:[1,0,1]
	v_pk_fma_f32 v[92:93], v[236:237], s[10:11], v[92:93] op_sel_hi:[1,0,1]
	global_store_dwordx4 v132, v[90:93], s[62:63] offset:16
	s_waitcnt vmcnt(3)
	v_pk_add_f32 v[238:239], v[238:239], v[142:143] op_sel_hi:[1,0] neg_lo:[0,1] neg_hi:[0,1]
	v_pk_add_f32 v[240:241], v[240:241], v[142:143] op_sel_hi:[1,0] neg_lo:[0,1] neg_hi:[0,1]
	v_pk_mul_f32 v[238:239], v[238:239], v[142:143] op_sel:[0,1]
	v_pk_mul_f32 v[240:241], v[240:241], v[142:143] op_sel:[0,1]
	v_pk_fma_f32 v[238:239], v[238:239], v[144:145], v[148:149]
	v_pk_fma_f32 v[240:241], v[240:241], v[146:147], v[150:151]
	v_pk_fma_f32 v[74:75], v[238:239], s[10:11], v[74:75] op_sel_hi:[1,0,1]
	v_pk_fma_f32 v[76:77], v[240:241], s[10:11], v[76:77] op_sel_hi:[1,0,1]
	global_store_dwordx4 v133, v[74:77], s[62:63] offset:16
	global_load_dwordx4 v[144:147], v0, s[58:59] offset:128
	global_load_dwordx4 v[148:151], v0, s[60:61] offset:128
	global_load_dwordx4 v[158:161], v130, s[62:63] offset:128
	global_load_dwordx4 v[162:165], v131, s[62:63] offset:128
	global_load_dwordx4 v[234:237], v132, s[62:63] offset:128
	global_load_dwordx4 v[238:241], v133, s[62:63] offset:128
	s_waitcnt vmcnt(3)
	v_pk_add_f32 v[158:159], v[158:159], v[134:135] op_sel_hi:[1,0] neg_lo:[0,1] neg_hi:[0,1]
	v_pk_add_f32 v[160:161], v[160:161], v[134:135] op_sel_hi:[1,0] neg_lo:[0,1] neg_hi:[0,1]
	v_pk_mul_f32 v[158:159], v[158:159], v[134:135] op_sel:[0,1]
	v_pk_mul_f32 v[160:161], v[160:161], v[134:135] op_sel:[0,1]
	v_pk_fma_f32 v[158:159], v[158:159], v[144:145], v[148:149]
	v_pk_fma_f32 v[160:161], v[160:161], v[146:147], v[150:151]
	v_pk_fma_f32 v[118:119], v[158:159], s[10:11], v[118:119] op_sel_hi:[1,0,1]
	v_pk_fma_f32 v[120:121], v[160:161], s[10:11], v[120:121] op_sel_hi:[1,0,1]
	global_store_dwordx4 v130, v[118:121], s[62:63] offset:128
	s_waitcnt vmcnt(3)
	v_pk_add_f32 v[162:163], v[162:163], v[136:137] op_sel_hi:[1,0] neg_lo:[0,1] neg_hi:[0,1]
	v_pk_add_f32 v[164:165], v[164:165], v[136:137] op_sel_hi:[1,0] neg_lo:[0,1] neg_hi:[0,1]
	v_pk_mul_f32 v[162:163], v[162:163], v[136:137] op_sel:[0,1]
	v_pk_mul_f32 v[164:165], v[164:165], v[136:137] op_sel:[0,1]
	v_pk_fma_f32 v[162:163], v[162:163], v[144:145], v[148:149]
	v_pk_fma_f32 v[164:165], v[164:165], v[146:147], v[150:151]
	v_pk_fma_f32 v[102:103], v[162:163], s[10:11], v[102:103] op_sel_hi:[1,0,1]
	v_pk_fma_f32 v[104:105], v[164:165], s[10:11], v[104:105] op_sel_hi:[1,0,1]
	global_store_dwordx4 v131, v[102:105], s[62:63] offset:128
	s_waitcnt vmcnt(3)
	v_pk_add_f32 v[234:235], v[234:235], v[140:141] op_sel_hi:[1,0] neg_lo:[0,1] neg_hi:[0,1]
	v_pk_add_f32 v[236:237], v[236:237], v[140:141] op_sel_hi:[1,0] neg_lo:[0,1] neg_hi:[0,1]
	v_pk_mul_f32 v[234:235], v[234:235], v[140:141] op_sel:[0,1]
	v_pk_mul_f32 v[236:237], v[236:237], v[140:141] op_sel:[0,1]
	v_pk_fma_f32 v[234:235], v[234:235], v[144:145], v[148:149]
	v_pk_fma_f32 v[236:237], v[236:237], v[146:147], v[150:151]
	v_pk_fma_f32 v[86:87], v[234:235], s[10:11], v[86:87] op_sel_hi:[1,0,1]
	v_pk_fma_f32 v[88:89], v[236:237], s[10:11], v[88:89] op_sel_hi:[1,0,1]
	global_store_dwordx4 v132, v[86:89], s[62:63] offset:128
	s_waitcnt vmcnt(3)
	v_pk_add_f32 v[238:239], v[238:239], v[142:143] op_sel_hi:[1,0] neg_lo:[0,1] neg_hi:[0,1]
	v_pk_add_f32 v[240:241], v[240:241], v[142:143] op_sel_hi:[1,0] neg_lo:[0,1] neg_hi:[0,1]
	v_pk_mul_f32 v[238:239], v[238:239], v[142:143] op_sel:[0,1]
	v_pk_mul_f32 v[240:241], v[240:241], v[142:143] op_sel:[0,1]
	v_pk_fma_f32 v[238:239], v[238:239], v[144:145], v[148:149]
	v_pk_fma_f32 v[240:241], v[240:241], v[146:147], v[150:151]
	v_pk_fma_f32 v[70:71], v[238:239], s[10:11], v[70:71] op_sel_hi:[1,0,1]
	v_pk_fma_f32 v[72:73], v[240:241], s[10:11], v[72:73] op_sel_hi:[1,0,1]
	global_store_dwordx4 v133, v[70:73], s[62:63] offset:128
	global_load_dwordx4 v[144:147], v0, s[58:59] offset:144
	global_load_dwordx4 v[148:151], v0, s[60:61] offset:144
	global_load_dwordx4 v[158:161], v130, s[62:63] offset:144
	global_load_dwordx4 v[162:165], v131, s[62:63] offset:144
	global_load_dwordx4 v[234:237], v132, s[62:63] offset:144
	global_load_dwordx4 v[238:241], v133, s[62:63] offset:144
	s_waitcnt vmcnt(3)
	v_pk_add_f32 v[158:159], v[158:159], v[134:135] op_sel_hi:[1,0] neg_lo:[0,1] neg_hi:[0,1]
	v_pk_add_f32 v[160:161], v[160:161], v[134:135] op_sel_hi:[1,0] neg_lo:[0,1] neg_hi:[0,1]
	v_pk_mul_f32 v[158:159], v[158:159], v[134:135] op_sel:[0,1]
	v_pk_mul_f32 v[160:161], v[160:161], v[134:135] op_sel:[0,1]
	v_pk_fma_f32 v[158:159], v[158:159], v[144:145], v[148:149]
	v_pk_fma_f32 v[160:161], v[160:161], v[146:147], v[150:151]
	v_pk_fma_f32 v[114:115], v[158:159], s[10:11], v[114:115] op_sel_hi:[1,0,1]
	v_pk_fma_f32 v[116:117], v[160:161], s[10:11], v[116:117] op_sel_hi:[1,0,1]
	global_store_dwordx4 v130, v[114:117], s[62:63] offset:144
	s_waitcnt vmcnt(3)
	v_pk_add_f32 v[162:163], v[162:163], v[136:137] op_sel_hi:[1,0] neg_lo:[0,1] neg_hi:[0,1]
	v_pk_add_f32 v[164:165], v[164:165], v[136:137] op_sel_hi:[1,0] neg_lo:[0,1] neg_hi:[0,1]
	v_pk_mul_f32 v[162:163], v[162:163], v[136:137] op_sel:[0,1]
	v_pk_mul_f32 v[164:165], v[164:165], v[136:137] op_sel:[0,1]
	v_pk_fma_f32 v[162:163], v[162:163], v[144:145], v[148:149]
	v_pk_fma_f32 v[164:165], v[164:165], v[146:147], v[150:151]
	v_pk_fma_f32 v[98:99], v[162:163], s[10:11], v[98:99] op_sel_hi:[1,0,1]
	v_pk_fma_f32 v[100:101], v[164:165], s[10:11], v[100:101] op_sel_hi:[1,0,1]
	global_store_dwordx4 v131, v[98:101], s[62:63] offset:144
	s_waitcnt vmcnt(3)
	v_pk_add_f32 v[234:235], v[234:235], v[140:141] op_sel_hi:[1,0] neg_lo:[0,1] neg_hi:[0,1]
	v_pk_add_f32 v[236:237], v[236:237], v[140:141] op_sel_hi:[1,0] neg_lo:[0,1] neg_hi:[0,1]
	v_pk_mul_f32 v[234:235], v[234:235], v[140:141] op_sel:[0,1]
	v_pk_mul_f32 v[236:237], v[236:237], v[140:141] op_sel:[0,1]
	v_pk_fma_f32 v[234:235], v[234:235], v[144:145], v[148:149]
	v_pk_fma_f32 v[236:237], v[236:237], v[146:147], v[150:151]
	v_pk_fma_f32 v[82:83], v[234:235], s[10:11], v[82:83] op_sel_hi:[1,0,1]
	v_pk_fma_f32 v[84:85], v[236:237], s[10:11], v[84:85] op_sel_hi:[1,0,1]
	global_store_dwordx4 v132, v[82:85], s[62:63] offset:144
	s_waitcnt vmcnt(3)
	v_pk_add_f32 v[238:239], v[238:239], v[142:143] op_sel_hi:[1,0] neg_lo:[0,1] neg_hi:[0,1]
	v_pk_add_f32 v[240:241], v[240:241], v[142:143] op_sel_hi:[1,0] neg_lo:[0,1] neg_hi:[0,1]
	v_pk_mul_f32 v[238:239], v[238:239], v[142:143] op_sel:[0,1]
	v_pk_mul_f32 v[240:241], v[240:241], v[142:143] op_sel:[0,1]
	v_pk_fma_f32 v[238:239], v[238:239], v[144:145], v[148:149]
	v_pk_fma_f32 v[240:241], v[240:241], v[146:147], v[150:151]
	v_pk_fma_f32 v[66:67], v[238:239], s[10:11], v[66:67] op_sel_hi:[1,0,1]
	v_pk_fma_f32 v[68:69], v[240:241], s[10:11], v[68:69] op_sel_hi:[1,0,1]
	global_store_dwordx4 v133, v[66:69], s[62:63] offset:144
.Lepi_done_157:
	s_andn2_b64 vcc, exec, s[44:45]
	s_mov_b64 s[38:39], -1
	s_cbranch_vccnz .LBB0_155
	v_mov_b32_e32 v0, v169
	v_mov_b32_e32 v67, v169
	s_mov_b64 s[38:39], 0
	v_lshrrev_b32_e32 v66, 3, v0
	v_lshlrev_b32_e32 v0, 3, v0
	v_lshrrev_b32_e32 v69, 3, v67
	v_lshlrev_b32_e32 v67, 3, v67
	v_add_u32_e32 v66, s8, v66
	v_and_b32_e32 v0, 56, v0
	v_add_u32_e32 v69, s9, v69
	v_and_b32_e32 v67, 56, v67
	v_lshl_or_b32 v0, v66, 10, v0
	v_lshl_or_b32 v72, v69, 10, v67
	v_add_u32_e32 v66, 0x8000, v0
	v_add_u32_e32 v68, 0x10000, v0
	v_add_u32_e32 v70, 0x18000, v0
	v_add_u32_e32 v74, 0x8000, v72
	v_add_u32_e32 v76, 0x10000, v72
	v_add_u32_e32 v78, 0x18000, v72
	s_branch .LBB0_155
